# merge phase (P3): row-statistics loads issued with the tile's first load batch instead of after the LDS barrier (one exposed round trip per tile fewer)
# speedup vs baseline: 1.0029x; 1.0029x over previous
.LBB0_474:
	s_ashr_i32 s11, s10, 31
	v_lshl_add_u64 v[120:121], s[10:11], 1, v[66:67]
	v_lshl_add_u64 v[0:1], v[120:121], 0, v[34:35]
	global_load_dwordx4 v[0:3], v[0:1], off nt
	v_lshl_add_u64 v[108:109], v[120:121], 0, v[58:59]
	v_lshl_add_u64 v[112:113], v[120:121], 0, v[60:61]
	v_lshl_add_u64 v[4:5], v[120:121], 0, v[36:37]
	global_load_dwordx4 v[108:111], v[108:109], off nt
	v_lshl_add_u64 v[116:117], v[120:121], 0, v[62:63]
	global_load_dwordx4 v[112:115], v[112:113], off nt
	v_lshl_add_u64 v[8:9], v[120:121], 0, v[38:39]
	global_load_dwordx4 v[4:7], v[4:5], off nt
	v_lshl_add_u64 v[12:13], v[120:121], 0, v[40:41]
	global_load_dwordx4 v[116:119], v[116:117], off nt
	v_lshl_add_u64 v[16:17], v[120:121], 0, v[42:43]
	global_load_dwordx4 v[8:11], v[8:9], off nt
	v_lshl_add_u64 v[20:21], v[120:121], 0, v[44:45]
	v_lshl_add_u64 v[24:25], v[120:121], 0, v[46:47]
	v_lshl_add_u64 v[28:29], v[120:121], 0, v[48:49]
	v_lshl_add_u64 v[70:71], v[120:121], 0, v[50:51]
	v_lshl_add_u64 v[74:75], v[120:121], 0, v[52:53]
	v_lshl_add_u64 v[78:79], v[120:121], 0, v[54:55]
	v_lshl_add_u64 v[104:105], v[120:121], 0, v[56:57]
	v_lshl_add_u64 v[120:121], v[120:121], 0, v[64:65]
	global_load_dwordx4 v[120:123], v[120:121], off nt
	v_add_u32_e32 v124, v82, v83
	global_load_dwordx4 v[12:15], v[12:13], off nt
	v_add_u32_e32 v125, 0x2100, v32
	global_load_dwordx4 v[16:19], v[16:17], off nt
	v_add_u32_e32 v126, 0x2108, v32
	global_load_dwordx4 v[20:23], v[20:21], off nt
	v_add_u32_e32 v127, 0x4200, v32
	global_load_dwordx4 v[24:27], v[24:25], off nt
	v_add_u32_e32 v128, 0x4208, v32
	global_load_dwordx4 v[28:31], v[28:29], off nt
	v_add_u32_e32 v129, 0x6300, v32
	global_load_dwordx4 v[70:73], v[70:71], off nt
	v_add_u32_e32 v130, 0x6308, v32
	global_load_dwordx4 v[74:77], v[74:75], off nt
	v_add_u32_e32 v131, 0x8400, v32
	global_load_dwordx4 v[78:81], v[78:79], off nt
	v_add_u32_e32 v132, 0x8408, v32
	global_load_dwordx4 v[104:107], v[104:105], off nt
	v_add_u32_e32 v133, 0xa500, v32
	v_add_u32_e32 v134, 0xa508, v32
	v_add_u32_e32 v135, 0xc600, v32
	v_add_u32_e32 v136, 0xc608, v32
	v_add_u32_e32 v137, 0xe700, v32
	v_add_u32_e32 v138, 0xe708, v32
	v_add_u32_e32 v139, 0x2100, v124
	v_add_u32_e32 v140, 0x2108, v124
	v_add_u32_e32 v141, 0x4200, v124
	v_add_u32_e32 v142, 0x4208, v124
	v_add_u32_e32 v143, 0x6300, v124
	v_add_u32_e32 v144, 0x6308, v124
	v_add_u32_e32 v145, 0x8400, v124
	v_add_u32_e32 v146, 0x8408, v124
	v_add_u32_e32 v147, 0xa500, v124
	s_lshl_b64 s[0:1], s[10:11], 3
	s_add_u32 s0, s9, s0
	s_addc_u32 s1, s18, s1
	s_add_i32 s12, s8, s10
	s_ashr_i32 s13, s12, 31
	s_add_i32 s15, s15, s14
	s_add_i32 s10, s10, s19
	global_load_dwordx4 v[214:217], v33, s[0:1]
	global_load_dwordx4 v[218:221], v33, s[0:1] offset:16
	global_load_dwordx4 v[222:225], v33, s[0:1] offset:32
	global_load_dwordx4 v[226:229], v33, s[0:1] offset:48
	s_waitcnt vmcnt(19)
	ds_write2_b32 v124, v0, v1 offset1:1
	ds_write2_b32 v124, v2, v3 offset0:2 offset1:3
	s_waitcnt vmcnt(16)
	ds_write2_b32 v139, v4, v5 offset1:1
	ds_write2_b32 v140, v6, v7 offset1:1
	s_waitcnt vmcnt(14)
	ds_write2_b32 v141, v8, v9 offset1:1
	ds_write2_b32 v142, v10, v11 offset1:1
	s_waitcnt vmcnt(12)
	ds_write2_b32 v143, v12, v13 offset1:1
	ds_write2_b32 v144, v14, v15 offset1:1
	s_waitcnt vmcnt(11)
	ds_write2_b32 v145, v16, v17 offset1:1
	ds_write2_b32 v146, v18, v19 offset1:1
	s_waitcnt vmcnt(10)
	ds_write2_b32 v147, v20, v21 offset1:1
	ds_write2_b32 v32, v22, v23 offset0:2 offset1:3
	s_waitcnt vmcnt(9)
	ds_write2_b32 v125, v24, v25 offset1:1
	ds_write2_b32 v126, v26, v27 offset1:1
	s_waitcnt vmcnt(8)
	ds_write2_b32 v127, v28, v29 offset1:1
	ds_write2_b32 v128, v30, v31 offset1:1
	s_waitcnt vmcnt(7)
	ds_write2_b32 v129, v70, v71 offset1:1
	ds_write2_b32 v130, v72, v73 offset1:1
	s_waitcnt vmcnt(6)
	ds_write2_b32 v131, v74, v75 offset1:1
	ds_write2_b32 v132, v76, v77 offset1:1
	s_waitcnt vmcnt(5)
	ds_write2_b32 v133, v78, v79 offset1:1
	ds_write2_b32 v134, v80, v81 offset1:1
	s_waitcnt vmcnt(4)
	ds_write2_b32 v135, v104, v105 offset1:1
	ds_write2_b32 v136, v106, v107 offset1:1
	ds_write2_b32 v137, v108, v109 offset1:1
	ds_write2_b32 v138, v110, v111 offset1:1
	v_add_u32_e32 v0, 0xe700, v95
	ds_write2_b32 v0, v112, v113 offset1:1
	v_add_u32_e32 v0, 0xe708, v95
	ds_write2_b32 v0, v114, v115 offset1:1
	v_add_u32_e32 v0, 0xe700, v96
	ds_write2_b32 v0, v116, v117 offset1:1
	v_add_u32_e32 v0, 0xe708, v96
	ds_write2_b32 v0, v118, v119 offset1:1
	v_add_u32_e32 v0, 0xe700, v97
	ds_write2_b32 v0, v120, v121 offset1:1
	v_add_u32_e32 v0, 0xe708, v97
	ds_write2_b32 v0, v122, v123 offset1:1
	s_waitcnt lgkmcnt(0)
	s_barrier
	v_add_u32_e32 v26, s16, v86
	v_add_u32_e32 v30, s16, v87
	v_add_u32_e32 v123, 0xc68c, v84
	s_waitcnt vmcnt(3)
	v_ffbh_u32_e32 v16, v215
	v_ffbh_u32_e32 v17, v217
	s_waitcnt vmcnt(2)
	v_ffbh_u32_e32 v18, v219
	s_waitcnt vmcnt(1)
	v_ffbh_u32_e32 v20, v223
	v_min_u32_e32 v16, 32, v16
	v_min_u32_e32 v17, 32, v17
	v_min_u32_e32 v18, 32, v18
	v_min_u32_e32 v20, 32, v20
	v_lshlrev_b64 v[0:1], v16, v[214:215]
	v_lshlrev_b64 v[2:3], v17, v[216:217]
	v_lshlrev_b64 v[4:5], v18, v[218:219]
	v_lshlrev_b64 v[8:9], v20, v[222:223]
	v_ffbh_u32_e32 v21, v225
	v_min_u32_e32 v0, 1, v0
	v_min_u32_e32 v2, 1, v2
	v_min_u32_e32 v4, 1, v4
	v_min_u32_e32 v8, 1, v8
	v_min_u32_e32 v21, 32, v21
	v_or_b32_e32 v0, v1, v0
	v_or_b32_e32 v1, v3, v2
	v_or_b32_e32 v2, v5, v4
	v_or_b32_e32 v4, v9, v8
	v_ffbh_u32_e32 v19, v221
	s_waitcnt vmcnt(0)
	v_ffbh_u32_e32 v23, v229
	v_lshlrev_b64 v[10:11], v21, v[224:225]
	v_cvt_f32_u32_e32 v4, v4
	v_ffbh_u32_e32 v22, v227
	v_min_u32_e32 v19, 32, v19
	v_min_u32_e32 v23, 32, v23
	v_min_u32_e32 v10, 1, v10
	v_min_u32_e32 v22, 32, v22
	v_lshlrev_b64 v[6:7], v19, v[220:221]
	v_lshlrev_b64 v[14:15], v23, v[228:229]
	v_or_b32_e32 v5, v11, v10
	v_sub_u32_e32 v20, 32, v20
	v_lshlrev_b64 v[12:13], v22, v[226:227]
	v_min_u32_e32 v6, 1, v6
	v_min_u32_e32 v14, 1, v14
	v_cvt_f32_u32_e32 v5, v5
	v_min_u32_e32 v12, 1, v12
	v_or_b32_e32 v3, v7, v6
	v_or_b32_e32 v7, v15, v14
	v_ldexp_f32 v4, v4, v20
	v_or_b32_e32 v6, v13, v12
	v_cvt_f32_u32_e32 v0, v0
	v_cvt_f32_u32_e32 v1, v1
	v_cvt_f32_u32_e32 v2, v2
	v_cvt_f32_u32_e32 v3, v3
	v_mul_f32_e32 v107, 0x2f800000, v4
	v_cvt_f32_u32_e32 v4, v7
	v_sub_u32_e32 v21, 32, v21
	v_cvt_f32_u32_e32 v6, v6
	v_ldexp_f32 v5, v5, v21
	v_sub_u32_e32 v16, 32, v16
	v_sub_u32_e32 v17, 32, v17
	v_sub_u32_e32 v18, 32, v18
	v_sub_u32_e32 v19, 32, v19
	v_mul_f32_e32 v106, 0x2f800000, v5
	v_sub_u32_e32 v5, 32, v23
	v_sub_u32_e32 v22, 32, v22
	v_ldexp_f32 v0, v0, v16
	v_ldexp_f32 v1, v1, v17
	v_ldexp_f32 v2, v2, v18
	v_ldexp_f32 v3, v3, v19
	v_ldexp_f32 v4, v4, v5
	v_ldexp_f32 v6, v6, v22
	v_mul_f32_e32 v174, 0x2f800000, v0
	v_mul_f32_e32 v155, 0x2f800000, v1
	v_mul_f32_e32 v122, 0x2f800000, v2
	v_mul_f32_e32 v108, 0x2f800000, v3
	ds_read2_b64 v[0:3], v84 offset1:1
	ds_read2_b32 v[70:71], v84 offset0:33 offset1:34
	v_mul_f32_e32 v104, 0x2f800000, v4
	v_add_u32_e32 v4, 0x4200, v84
	v_add_u32_e32 v8, 0x4284, v84
	v_mul_f32_e32 v105, 0x2f800000, v6
	ds_read2_b64 v[4:7], v4 offset1:1
	ds_read2_b32 v[72:73], v8 offset1:1
	ds_read2_b32 v[74:75], v84 offset0:35 offset1:36
	v_add_u32_e32 v14, 0x8484, v84
	v_add_u32_e32 v8, 0x8400, v84
	ds_read2_b32 v[110:111], v14 offset1:1
	ds_read2_b32 v[116:117], v26 offset1:1
	ds_read2_b64 v[8:11], v8 offset1:1
	s_waitcnt lgkmcnt(6)
	v_lshlrev_b32_e32 v173, 16, v70
	s_waitcnt lgkmcnt(4)
	v_lshlrev_b32_e32 v202, 16, v72
	v_lshlrev_b32_e32 v172, 16, v0
	v_mul_f32_e32 v12, v173, v173
	v_lshlrev_b32_e32 v197, 16, v4
	v_mul_f32_e32 v13, v202, v202
	v_fmac_f32_e32 v12, v172, v172
	v_fmac_f32_e32 v13, v197, v197
	v_add_u32_e32 v18, 0xc684, v84
	v_add_u32_e32 v22, s16, v85
	v_add_f32_e32 v16, v12, v13
	v_add_u32_e32 v12, 0xc600, v84
	ds_read2_b32 v[112:113], v18 offset1:1
	ds_read2_b32 v[114:115], v22 offset1:1
	s_waitcnt lgkmcnt(4)
	v_lshlrev_b32_e32 v203, 16, v110
	ds_read2_b64 v[12:15], v12 offset1:1
	s_waitcnt lgkmcnt(3)
	v_lshlrev_b32_e32 v198, 16, v8
	v_mul_f32_e32 v17, v203, v203
	v_fmac_f32_e32 v17, v198, v198
	v_add_f32_e32 v20, v16, v17
	ds_read2_b64 v[16:19], v98 offset1:1
	ds_read2_b32 v[118:119], v30 offset1:1
	s_waitcnt lgkmcnt(4)
	v_lshlrev_b32_e32 v201, 16, v112
	s_waitcnt lgkmcnt(2)
	v_lshlrev_b32_e32 v199, 16, v12
	v_mul_f32_e32 v21, v201, v201
	v_lshlrev_b32_e32 v200, 16, v114
	v_fmac_f32_e32 v21, v199, v199
	s_waitcnt lgkmcnt(1)
	v_lshlrev_b32_e32 v195, 16, v16
	v_mul_f32_e32 v25, v200, v200
	v_add_f32_e32 v24, v20, v21
	ds_read2_b64 v[20:23], v99 offset1:1
	v_fmac_f32_e32 v25, v195, v195
	v_add_f32_e32 v28, v24, v25
	ds_read2_b64 v[24:27], v100 offset1:1
	v_and_b32_e32 v190, 0xffff0000, v70
	v_and_b32_e32 v188, 0xffff0000, v72
	v_and_b32_e32 v189, 0xffff0000, v0
	v_mul_f32_e32 v0, v190, v190
	v_and_b32_e32 v187, 0xffff0000, v4
	v_mul_f32_e32 v4, v188, v188
	v_lshlrev_b32_e32 v196, 16, v116
	v_fmac_f32_e32 v0, v189, v189
	v_fmac_f32_e32 v4, v187, v187
	v_and_b32_e32 v186, 0xffff0000, v110
	s_waitcnt lgkmcnt(1)
	v_lshlrev_b32_e32 v193, 16, v20
	v_mul_f32_e32 v29, v196, v196
	v_lshlrev_b32_e32 v194, 16, v118
	v_add_f32_e32 v0, v0, v4
	v_and_b32_e32 v185, 0xffff0000, v8
	v_mul_f32_e32 v4, v186, v186
	v_fmac_f32_e32 v29, v193, v193
	s_waitcnt lgkmcnt(0)
	v_lshlrev_b32_e32 v192, 16, v24
	v_mul_f32_e32 v77, v194, v194
	v_fmac_f32_e32 v4, v185, v185
	v_and_b32_e32 v184, 0xffff0000, v112
	v_add_f32_e32 v76, v28, v29
	v_fmac_f32_e32 v77, v192, v192
	v_add_f32_e32 v0, v0, v4
	v_and_b32_e32 v183, 0xffff0000, v12
	v_mul_f32_e32 v4, v184, v184
	v_add_f32_e32 v109, v76, v77
	v_add_u32_e32 v76, s16, v88
	v_fmac_f32_e32 v4, v183, v183
	v_and_b32_e32 v182, 0xffff0000, v114
	ds_read2_b64 v[28:31], v101 offset1:1
	ds_read2_b32 v[120:121], v76 offset1:1
	v_add_f32_e32 v0, v0, v4
	v_and_b32_e32 v181, 0xffff0000, v16
	v_mul_f32_e32 v4, v182, v182
	v_fmac_f32_e32 v4, v181, v181
	v_and_b32_e32 v180, 0xffff0000, v116
	v_add_f32_e32 v0, v0, v4
	v_and_b32_e32 v179, 0xffff0000, v20
	v_mul_f32_e32 v4, v180, v180
	v_fmac_f32_e32 v4, v179, v179
	v_and_b32_e32 v178, 0xffff0000, v118
	v_add_f32_e32 v0, v0, v4
	v_and_b32_e32 v177, 0xffff0000, v24
	v_mul_f32_e32 v4, v178, v178
	v_fmac_f32_e32 v4, v177, v177
	s_waitcnt lgkmcnt(0)
	v_and_b32_e32 v176, 0xffff0000, v120
	v_add_f32_e32 v0, v0, v4
	v_and_b32_e32 v175, 0xffff0000, v28
	v_mul_f32_e32 v4, v176, v176
	v_fmac_f32_e32 v4, v175, v175
	v_lshlrev_b32_e32 v171, 16, v71
	v_lshlrev_b32_e32 v169, 16, v73
	v_add_f32_e32 v210, v0, v4
	v_lshlrev_b32_e32 v170, 16, v1
	v_mul_f32_e32 v0, v171, v171
	v_lshlrev_b32_e32 v168, 16, v5
	v_mul_f32_e32 v4, v169, v169
	v_fmac_f32_e32 v0, v170, v170
	v_fmac_f32_e32 v4, v168, v168
	v_lshlrev_b32_e32 v167, 16, v111
	v_add_f32_e32 v0, v0, v4
	v_lshlrev_b32_e32 v166, 16, v9
	v_mul_f32_e32 v4, v167, v167
	v_fmac_f32_e32 v4, v166, v166
	v_lshlrev_b32_e32 v165, 16, v113
	v_add_f32_e32 v0, v0, v4
	v_lshlrev_b32_e32 v164, 16, v13
	v_mul_f32_e32 v4, v165, v165
	v_fmac_f32_e32 v4, v164, v164
	v_lshlrev_b32_e32 v163, 16, v115
	v_add_f32_e32 v0, v0, v4
	v_lshlrev_b32_e32 v162, 16, v17
	v_mul_f32_e32 v4, v163, v163
	v_fmac_f32_e32 v4, v162, v162
	v_lshlrev_b32_e32 v161, 16, v117
	v_add_f32_e32 v0, v0, v4
	v_lshlrev_b32_e32 v160, 16, v21
	v_mul_f32_e32 v4, v161, v161
	v_fmac_f32_e32 v4, v160, v160
	v_lshlrev_b32_e32 v159, 16, v119
	v_add_f32_e32 v0, v0, v4
	v_lshlrev_b32_e32 v158, 16, v25
	v_mul_f32_e32 v4, v159, v159
	v_fmac_f32_e32 v4, v158, v158
	v_lshlrev_b32_e32 v157, 16, v121
	v_add_f32_e32 v0, v0, v4
	v_lshlrev_b32_e32 v156, 16, v29
	v_mul_f32_e32 v4, v157, v157
	v_fmac_f32_e32 v4, v156, v156
	v_and_b32_e32 v154, 0xffff0000, v71
	v_and_b32_e32 v152, 0xffff0000, v73
	v_add_f32_e32 v211, v0, v4
	v_and_b32_e32 v153, 0xffff0000, v1
	v_mul_f32_e32 v0, v154, v154
	v_and_b32_e32 v151, 0xffff0000, v5
	v_mul_f32_e32 v1, v152, v152
	v_fmac_f32_e32 v0, v153, v153
	v_fmac_f32_e32 v1, v151, v151
	v_and_b32_e32 v150, 0xffff0000, v111
	v_add_f32_e32 v0, v0, v1
	v_and_b32_e32 v149, 0xffff0000, v9
	v_mul_f32_e32 v1, v150, v150
	v_fmac_f32_e32 v1, v149, v149
	v_and_b32_e32 v148, 0xffff0000, v113
	v_add_f32_e32 v0, v0, v1
	v_and_b32_e32 v147, 0xffff0000, v13
	v_mul_f32_e32 v1, v148, v148
	v_fmac_f32_e32 v1, v147, v147
	v_and_b32_e32 v146, 0xffff0000, v115
	v_add_f32_e32 v0, v0, v1
	v_and_b32_e32 v145, 0xffff0000, v17
	v_mul_f32_e32 v1, v146, v146
	v_fmac_f32_e32 v1, v145, v145
	v_and_b32_e32 v144, 0xffff0000, v117
	v_add_f32_e32 v0, v0, v1
	v_and_b32_e32 v143, 0xffff0000, v21
	v_mul_f32_e32 v1, v144, v144
	v_add_u32_e32 v76, 0x428c, v84
	v_add_u32_e32 v77, 0x848c, v84
	v_fmac_f32_e32 v1, v143, v143
	v_and_b32_e32 v142, 0xffff0000, v119
	ds_read2_b32 v[80:81], v76 offset1:1
	ds_read2_b32 v[78:79], v77 offset1:1
	ds_read2_b32 v[76:77], v123 offset1:1
	v_add_f32_e32 v0, v0, v1
	v_and_b32_e32 v141, 0xffff0000, v25
	v_mul_f32_e32 v1, v142, v142
	v_fmac_f32_e32 v1, v141, v141
	v_and_b32_e32 v140, 0xffff0000, v121
	v_add_f32_e32 v0, v0, v1
	v_and_b32_e32 v139, 0xffff0000, v29
	v_mul_f32_e32 v1, v140, v140
	v_fmac_f32_e32 v1, v139, v139
	v_lshlrev_b32_e32 v133, 16, v74
	s_waitcnt lgkmcnt(2)
	v_lshlrev_b32_e32 v131, 16, v80
	v_add_f32_e32 v212, v0, v1
	v_lshlrev_b32_e32 v132, 16, v2
	v_mul_f32_e32 v0, v133, v133
	v_lshlrev_b32_e32 v130, 16, v6
	v_mul_f32_e32 v1, v131, v131
	v_fmac_f32_e32 v0, v132, v132
	v_fmac_f32_e32 v1, v130, v130
	s_waitcnt lgkmcnt(1)
	v_lshlrev_b32_e32 v129, 16, v78
	v_add_f32_e32 v0, v0, v1
	v_lshlrev_b32_e32 v128, 16, v10
	v_mul_f32_e32 v1, v129, v129
	v_fmac_f32_e32 v1, v128, v128
	s_waitcnt lgkmcnt(0)
	v_lshlrev_b32_e32 v127, 16, v76
	v_add_f32_e32 v0, v0, v1
	v_lshlrev_b32_e32 v126, 16, v14
	v_mul_f32_e32 v1, v127, v127
	v_fmac_f32_e32 v1, v126, v126
	v_add_f32_e32 v8, v0, v1
	v_add_u32_e32 v0, s17, v85
	ds_read2_b32 v[0:1], v0 offset1:1
	v_and_b32_e32 v121, 0xffff0000, v74
	v_and_b32_e32 v119, 0xffff0000, v80
	v_lshlrev_b32_e32 v204, 16, v120
	v_and_b32_e32 v120, 0xffff0000, v2
	v_mul_f32_e32 v2, v121, v121
	v_and_b32_e32 v118, 0xffff0000, v6
	v_mul_f32_e32 v6, v119, v119
	v_fmac_f32_e32 v2, v120, v120
	v_fmac_f32_e32 v6, v118, v118
	v_and_b32_e32 v117, 0xffff0000, v78
	v_add_u32_e32 v4, s17, v86
	v_add_f32_e32 v2, v2, v6
	v_and_b32_e32 v116, 0xffff0000, v10
	v_mul_f32_e32 v6, v117, v117
	v_add_u32_e32 v9, s17, v87
	v_add_u32_e32 v12, s17, v88
	ds_read2_b32 v[4:5], v4 offset1:1
	ds_read2_b32 v[206:207], v9 offset1:1
	ds_read2_b32 v[208:209], v12 offset1:1
	v_fmac_f32_e32 v6, v116, v116
	v_and_b32_e32 v115, 0xffff0000, v76
	v_add_f32_e32 v2, v2, v6
	v_and_b32_e32 v114, 0xffff0000, v14
	v_mul_f32_e32 v6, v115, v115
	s_waitcnt lgkmcnt(3)
	v_and_b32_e32 v113, 0xffff0000, v0
	v_lshlrev_b32_e32 v138, 16, v0
	v_fmac_f32_e32 v6, v114, v114
	v_and_b32_e32 v112, 0xffff0000, v18
	v_mul_f32_e32 v0, v113, v113
	v_lshlrev_b32_e32 v191, 16, v28
	v_mul_f32_e32 v123, v204, v204
	v_add_f32_e32 v2, v2, v6
	v_fmac_f32_e32 v0, v112, v112
	s_waitcnt lgkmcnt(2)
	v_and_b32_e32 v111, 0xffff0000, v4
	v_fmac_f32_e32 v123, v191, v191
	v_add_f32_e32 v0, v2, v0
	v_and_b32_e32 v110, 0xffff0000, v22
	v_mul_f32_e32 v2, v111, v111
	v_add_f32_e32 v205, v109, v123
	v_fmac_f32_e32 v2, v110, v110
	s_waitcnt lgkmcnt(1)
	v_and_b32_e32 v109, 0xffff0000, v206
	v_add_f32_e32 v0, v0, v2
	v_and_b32_e32 v80, 0xffff0000, v26
	v_mul_f32_e32 v2, v109, v109
	v_fmac_f32_e32 v2, v80, v80
	s_waitcnt lgkmcnt(0)
	v_and_b32_e32 v78, 0xffff0000, v208
	v_add_f32_e32 v0, v0, v2
	v_and_b32_e32 v76, 0xffff0000, v30
	v_mul_f32_e32 v2, v78, v78
	v_fmac_f32_e32 v2, v76, v76
	v_lshlrev_b32_e32 v74, 16, v75
	v_lshlrev_b32_e32 v72, 16, v81
	v_lshlrev_b32_e32 v135, 16, v206
	v_add_f32_e32 v206, v0, v2
	v_lshlrev_b32_e32 v73, 16, v3
	v_mul_f32_e32 v0, v74, v74
	v_lshlrev_b32_e32 v71, 16, v7
	v_mul_f32_e32 v2, v72, v72
	v_fmac_f32_e32 v0, v73, v73
	v_fmac_f32_e32 v2, v71, v71
	v_lshlrev_b32_e32 v70, 16, v79
	v_lshlrev_b32_e32 v124, 16, v30
	v_add_f32_e32 v0, v0, v2
	v_lshlrev_b32_e32 v30, 16, v11
	v_mul_f32_e32 v2, v70, v70
	v_fmac_f32_e32 v2, v30, v30
	v_lshlrev_b32_e32 v29, 16, v77
	v_add_f32_e32 v0, v0, v2
	v_lshlrev_b32_e32 v28, 16, v15
	v_mul_f32_e32 v2, v29, v29
	v_lshlrev_b32_e32 v134, 16, v26
	v_fmac_f32_e32 v2, v28, v28
	v_lshlrev_b32_e32 v26, 16, v1
	v_add_f32_e32 v0, v0, v2
	v_lshlrev_b32_e32 v25, 16, v19
	v_mul_f32_e32 v2, v26, v26
	v_fmac_f32_e32 v2, v25, v25
	v_lshlrev_b32_e32 v24, 16, v5
	v_lshlrev_b32_e32 v136, 16, v22
	v_add_f32_e32 v0, v0, v2
	v_lshlrev_b32_e32 v22, 16, v23
	v_mul_f32_e32 v2, v24, v24
	v_lshlrev_b32_e32 v123, 16, v18
	v_mul_f32_e32 v9, v138, v138
	v_fmac_f32_e32 v2, v22, v22
	v_lshlrev_b32_e32 v21, 16, v207
	v_fmac_f32_e32 v9, v123, v123
	v_lshlrev_b32_e32 v137, 16, v4
	v_add_f32_e32 v0, v0, v2
	v_lshlrev_b32_e32 v20, 16, v27
	v_mul_f32_e32 v2, v21, v21
	v_add_f32_e32 v8, v8, v9
	v_mul_f32_e32 v9, v137, v137
	v_fmac_f32_e32 v2, v20, v20
	v_lshlrev_b32_e32 v18, 16, v209
	v_fmac_f32_e32 v9, v136, v136
	v_add_f32_e32 v0, v0, v2
	v_lshlrev_b32_e32 v17, 16, v31
	v_mul_f32_e32 v2, v18, v18
	v_add_f32_e32 v8, v8, v9
	v_mul_f32_e32 v9, v135, v135
	v_fmac_f32_e32 v2, v17, v17
	v_and_b32_e32 v16, 0xffff0000, v75
	v_and_b32_e32 v13, 0xffff0000, v81
	v_fmac_f32_e32 v9, v134, v134
	v_lshlrev_b32_e32 v125, 16, v208
	v_add_f32_e32 v208, v0, v2
	v_and_b32_e32 v14, 0xffff0000, v3
	v_mul_f32_e32 v0, v16, v16
	v_and_b32_e32 v12, 0xffff0000, v7
	v_mul_f32_e32 v2, v13, v13
	v_add_f32_e32 v8, v8, v9
	v_mul_f32_e32 v9, v125, v125
	v_fmac_f32_e32 v0, v14, v14
	v_fmac_f32_e32 v2, v12, v12
	v_and_b32_e32 v10, 0xffff0000, v11
	v_and_b32_e32 v11, 0xffff0000, v79
	v_fmac_f32_e32 v9, v124, v124
	v_add_f32_e32 v0, v0, v2
	v_mul_f32_e32 v2, v11, v11
	v_add_f32_e32 v213, v8, v9
	v_fmac_f32_e32 v2, v10, v10
	v_and_b32_e32 v9, 0xffff0000, v77
	v_add_f32_e32 v0, v0, v2
	v_and_b32_e32 v8, 0xffff0000, v15
	v_mul_f32_e32 v2, v9, v9
	v_and_b32_e32 v7, 0xffff0000, v1
	v_fmac_f32_e32 v2, v8, v8
	v_and_b32_e32 v6, 0xffff0000, v19
	v_mul_f32_e32 v1, v7, v7
	v_add_f32_e32 v0, v0, v2
	v_fmac_f32_e32 v1, v6, v6
	v_and_b32_e32 v5, 0xffff0000, v5
	v_add_f32_e32 v0, v0, v1
	v_and_b32_e32 v4, 0xffff0000, v23
	v_mul_f32_e32 v1, v5, v5
	v_fmac_f32_e32 v1, v4, v4
	v_and_b32_e32 v3, 0xffff0000, v207
	v_add_f32_e32 v0, v0, v1
	v_and_b32_e32 v2, 0xffff0000, v27
	v_mul_f32_e32 v1, v3, v3
	v_fmac_f32_e32 v1, v2, v2
	v_add_f32_e32 v15, v0, v1
	v_and_b32_e32 v0, 0xffff0000, v31
	ds_bpermute_b32 v23, v89, v205
	ds_bpermute_b32 v27, v89, v210
	ds_bpermute_b32 v31, v89, v211
	v_and_b32_e32 v1, 0xffff0000, v209
	ds_bpermute_b32 v77, v89, v206
	v_mul_f32_e32 v19, v1, v1
	v_fmac_f32_e32 v19, v0, v0
	ds_bpermute_b32 v75, v89, v213
	v_add_f32_e32 v15, v15, v19
	ds_bpermute_b32 v79, v89, v208
	s_waitcnt lgkmcnt(5)
	v_add_f32_e32 v19, v205, v23
	s_waitcnt lgkmcnt(4)
	v_add_f32_e32 v23, v210, v27
	s_waitcnt lgkmcnt(3)
	v_add_f32_e32 v27, v211, v31
	ds_bpermute_b32 v81, v89, v15
	ds_bpermute_b32 v31, v89, v212
	s_waitcnt lgkmcnt(4)
	v_add_f32_e32 v77, v206, v77
	ds_bpermute_b32 v206, v90, v27
	s_waitcnt lgkmcnt(4)
	v_add_f32_e32 v75, v213, v75
	ds_bpermute_b32 v205, v90, v23
	s_waitcnt lgkmcnt(4)
	v_add_f32_e32 v79, v208, v79
	ds_bpermute_b32 v208, v90, v75
	s_waitcnt lgkmcnt(4)
	v_add_f32_e32 v15, v15, v81
	s_waitcnt lgkmcnt(3)
	v_add_f32_e32 v31, v212, v31
	ds_bpermute_b32 v81, v90, v19
	s_waitcnt lgkmcnt(3)
	v_add_f32_e32 v27, v27, v206
	ds_bpermute_b32 v206, v90, v15
	ds_bpermute_b32 v207, v90, v31
	s_waitcnt lgkmcnt(4)
	v_add_f32_e32 v23, v23, v205
	ds_bpermute_b32 v205, v90, v79
	s_waitcnt lgkmcnt(4)
	v_add_f32_e32 v75, v75, v208
	ds_bpermute_b32 v208, v91, v23
	s_waitcnt lgkmcnt(4)
	v_add_f32_e32 v19, v19, v81
	ds_bpermute_b32 v81, v90, v77
	s_waitcnt lgkmcnt(4)
	v_add_f32_e32 v15, v15, v206
	ds_bpermute_b32 v206, v91, v75
	s_waitcnt lgkmcnt(4)
	v_add_f32_e32 v31, v31, v207
	ds_bpermute_b32 v207, v91, v19
	s_waitcnt lgkmcnt(4)
	v_add_f32_e32 v79, v79, v205
	ds_bpermute_b32 v205, v91, v31
	s_waitcnt lgkmcnt(4)
	v_add_f32_e32 v23, v23, v208
	ds_bpermute_b32 v208, v91, v79
	s_waitcnt lgkmcnt(4)
	v_add_f32_e32 v77, v77, v81
	ds_bpermute_b32 v81, v91, v27
	s_waitcnt lgkmcnt(4)
	v_add_f32_e32 v75, v75, v206
	ds_bpermute_b32 v206, v92, v23
	s_waitcnt lgkmcnt(4)
	v_add_f32_e32 v19, v19, v207
	ds_bpermute_b32 v207, v91, v77
	s_waitcnt lgkmcnt(4)
	v_add_f32_e32 v31, v31, v205
	ds_bpermute_b32 v205, v92, v19
	s_waitcnt lgkmcnt(4)
	v_add_f32_e32 v79, v79, v208
	ds_bpermute_b32 v208, v92, v31
	s_waitcnt lgkmcnt(4)
	v_add_f32_e32 v27, v27, v81
	s_waitcnt lgkmcnt(3)
	v_add_f32_e32 v23, v23, v206
	ds_bpermute_b32 v206, v92, v79
	s_waitcnt lgkmcnt(3)
	v_add_f32_e32 v77, v77, v207
	ds_bpermute_b32 v81, v91, v15
	ds_bpermute_b32 v207, v92, v27
	s_waitcnt lgkmcnt(4)
	v_add_f32_e32 v19, v19, v205
	ds_bpermute_b32 v205, v92, v77
	s_waitcnt lgkmcnt(4)
	v_add_f32_e32 v31, v31, v208
	ds_bpermute_b32 v208, v93, v19
	s_waitcnt lgkmcnt(4)
	v_add_f32_e32 v79, v79, v206
	ds_bpermute_b32 v206, v93, v31
	s_waitcnt lgkmcnt(4)
	v_add_f32_e32 v15, v15, v81
	s_waitcnt lgkmcnt(3)
	v_add_f32_e32 v27, v27, v207
	ds_bpermute_b32 v81, v92, v75
	ds_bpermute_b32 v207, v92, v15
	s_waitcnt lgkmcnt(4)
	v_add_f32_e32 v77, v77, v205
	ds_bpermute_b32 v205, v93, v27
	s_waitcnt lgkmcnt(4)
	v_add_f32_e32 v19, v19, v208
	ds_bpermute_b32 v208, v93, v77
	s_waitcnt lgkmcnt(4)
	v_add_f32_e32 v31, v31, v206
	ds_bpermute_b32 v206, v94, v19
	s_waitcnt lgkmcnt(4)
	v_add_f32_e32 v75, v75, v81
	s_waitcnt lgkmcnt(3)
	v_add_f32_e32 v15, v15, v207
	ds_bpermute_b32 v207, v93, v75
	s_waitcnt lgkmcnt(3)
	v_add_f32_e32 v27, v27, v205
	ds_bpermute_b32 v81, v93, v23
	s_waitcnt lgkmcnt(3)
	v_add_f32_e32 v77, v77, v208
	ds_bpermute_b32 v205, v93, v15
	ds_bpermute_b32 v208, v94, v27
	s_waitcnt lgkmcnt(4)
	v_add_f32_e32 v19, v19, v206
	v_fmamk_f32 v19, v19, 0x3a800000, v102
	s_waitcnt lgkmcnt(3)
	v_add_f32_e32 v75, v75, v207
	v_mul_f32_e32 v206, 0x4f800000, v19
	v_cmp_gt_f32_e32 vcc, s23, v19
	s_waitcnt lgkmcnt(2)
	v_add_f32_e32 v23, v23, v81
	s_waitcnt lgkmcnt(1)
	v_add_f32_e32 v15, v15, v205
	s_waitcnt lgkmcnt(0)
	v_add_f32_e32 v205, v27, v208
	ds_bpermute_b32 v27, v94, v75
	v_cndmask_b32_e32 v19, v19, v206, vcc
	ds_bpermute_b32 v81, v93, v79
	ds_bpermute_b32 v207, v94, v23
	v_sqrt_f32_e32 v206, v19
	s_waitcnt lgkmcnt(2)
	v_add_f32_e32 v27, v75, v27
	v_fmamk_f32 v174, v174, 0x3a800000, v102
	s_waitcnt lgkmcnt(1)
	v_add_f32_e32 v79, v79, v81
	v_add_u32_e32 v75, -1, v206
	s_waitcnt lgkmcnt(0)
	v_add_f32_e32 v81, v23, v207
	v_fma_f32 v207, -v75, v206, v19
	v_cmp_ge_f32_e64 s[4:5], 0, v207
	v_add_u32_e32 v207, 1, v206
	v_mul_f32_e32 v210, 0x4f800000, v174
	v_cndmask_b32_e64 v75, v206, v75, s[4:5]
	v_fma_f32 v206, -v207, v206, v19
	v_cmp_lt_f32_e64 s[4:5], 0, v206
	ds_bpermute_b32 v23, v94, v31
	v_fmamk_f32 v155, v155, 0x3a800000, v102
	v_cndmask_b32_e64 v75, v75, v207, s[4:5]
	v_mul_f32_e32 v206, 0x37800000, v75
	v_cndmask_b32_e32 v75, v75, v206, vcc
	v_cmp_class_f32_e32 vcc, v19, v103
	v_cmp_gt_f32_e64 s[4:5], s23, v174
	s_waitcnt lgkmcnt(0)
	v_add_f32_e32 v31, v31, v23
	v_cndmask_b32_e32 v19, v75, v19, vcc
	v_div_scale_f32 v75, s[0:1], v19, v19, 1.0
	v_rcp_f32_e32 v206, v75
	v_cndmask_b32_e64 v174, v174, v210, s[4:5]
	v_sqrt_f32_e32 v210, v174
	ds_bpermute_b32 v23, v94, v77
	v_fma_f32 v208, -v75, v206, 1.0
	v_fmac_f32_e32 v206, v208, v206
	v_div_scale_f32 v208, vcc, 1.0, v19, 1.0
	v_mul_f32_e32 v209, v208, v206
	v_fma_f32 v211, -v75, v209, v208
	v_fmac_f32_e32 v209, v211, v206
	v_fma_f32 v75, -v75, v209, v208
	v_add_u32_e32 v208, -1, v210
	v_fma_f32 v211, -v208, v210, v174
	v_cmp_ge_f32_e64 s[6:7], 0, v211
	v_add_u32_e32 v211, 1, v210
	v_div_fmas_f32 v75, v75, v206, v209
	v_cndmask_b32_e64 v208, v210, v208, s[6:7]
	v_fma_f32 v210, -v211, v210, v174
	v_cmp_lt_f32_e64 s[6:7], 0, v210
	v_div_fixup_f32 v75, v75, v19, 1.0
	s_waitcnt lgkmcnt(0)
	v_add_f32_e32 v23, v77, v23
	v_cndmask_b32_e64 v208, v208, v211, s[6:7]
	v_mul_f32_e32 v210, 0x37800000, v208
	v_cndmask_b32_e64 v208, v208, v210, s[4:5]
	v_cmp_class_f32_e64 s[4:5], v174, v103
	ds_bpermute_b32 v77, v94, v79
	ds_bpermute_b32 v207, v94, v15
	v_cndmask_b32_e64 v174, v208, v174, s[4:5]
	v_div_scale_f32 v208, s[0:1], v174, v174, 1.0
	v_rcp_f32_e32 v210, v208
	s_waitcnt lgkmcnt(0)
	v_add_f32_e32 v15, v15, v207
	v_fmamk_f32 v122, v122, 0x3a800000, v102
	v_fmamk_f32 v31, v31, 0x3a800000, v102
	v_fma_f32 v19, -v208, v210, 1.0
	v_fmac_f32_e32 v210, v19, v210
	v_div_scale_f32 v19, vcc, 1.0, v174, 1.0
	v_mul_f32_e32 v206, v19, v210
	v_fma_f32 v209, -v208, v206, v19
	v_fmac_f32_e32 v206, v209, v210
	v_fma_f32 v19, -v208, v206, v19
	v_div_fmas_f32 v19, v19, v210, v206
	v_div_fixup_f32 v174, v19, v174, 1.0
	v_div_scale_f32 v206, s[0:1], v174, v174, v75
	v_rcp_f32_e32 v208, v206
	v_add_f32_e32 v19, v79, v77
	s_lshl_b64 s[0:1], s[12:13], 12
	v_fmamk_f32 v108, v108, 0x3a800000, v102
	v_fma_f32 v77, -v206, v208, 1.0
	v_fmac_f32_e32 v208, v77, v208
	v_div_scale_f32 v77, vcc, v75, v174, v75
	v_mul_f32_e32 v79, v77, v208
	v_fma_f32 v207, -v206, v79, v77
	v_fmac_f32_e32 v79, v207, v208
	v_fma_f32 v77, -v206, v79, v77
	v_div_fmas_f32 v77, v77, v208, v79
	v_div_fixup_f32 v75, v77, v174, v75
	v_mul_f32_e32 v77, v75, v172
	v_mul_f32_e32 v79, v75, v173
	v_bfe_u32 v172, v77, 16, 1
	v_add3_u32 v77, v77, v172, s24
	v_bfe_u32 v172, v79, 16, 1
	v_lshrrev_b32_e32 v77, 16, v77
	v_add3_u32 v79, v79, v172, s24
	v_lshl_add_u64 v[206:207], v[68:69], 0, s[0:1]
	v_and_or_b32 v77, v79, s22, v77
	global_store_dword v[206:207], v77, off offset:2048
	v_mul_f32_e32 v77, v75, v197
	v_mul_f32_e32 v79, v75, v202
	v_bfe_u32 v172, v77, 16, 1
	v_add3_u32 v77, v77, v172, s24
	v_bfe_u32 v172, v79, 16, 1
	v_lshrrev_b32_e32 v77, 16, v77
	v_add3_u32 v79, v79, v172, s24
	v_and_or_b32 v77, v79, s22, v77
	global_store_dword v[206:207], v77, off offset:2304
	v_mul_f32_e32 v77, v75, v198
	v_mul_f32_e32 v79, v75, v203
	v_bfe_u32 v172, v77, 16, 1
	v_add3_u32 v77, v77, v172, s24
	v_bfe_u32 v172, v79, 16, 1
	v_lshrrev_b32_e32 v77, 16, v77
	v_add3_u32 v79, v79, v172, s24
	v_and_or_b32 v77, v79, s22, v77
	global_store_dword v[206:207], v77, off offset:2560
	v_mul_f32_e32 v77, v75, v199
	v_mul_f32_e32 v79, v75, v201
	v_bfe_u32 v172, v77, 16, 1
	v_add3_u32 v77, v77, v172, s24
	v_bfe_u32 v172, v79, 16, 1
	v_lshrrev_b32_e32 v77, 16, v77
	v_add3_u32 v79, v79, v172, s24
	v_and_or_b32 v77, v79, s22, v77
	global_store_dword v[206:207], v77, off offset:2816
	v_mul_f32_e32 v77, v75, v195
	v_mul_f32_e32 v79, v75, v200
	v_bfe_u32 v172, v77, 16, 1
	v_add3_u32 v77, v77, v172, s24
	v_bfe_u32 v172, v79, 16, 1
	v_lshrrev_b32_e32 v77, 16, v77
	v_add3_u32 v79, v79, v172, s24
	v_and_or_b32 v77, v79, s22, v77
	global_store_dword v[206:207], v77, off offset:3072
	v_mul_f32_e32 v77, v75, v193
	v_mul_f32_e32 v79, v75, v196
	v_bfe_u32 v172, v77, 16, 1
	v_add3_u32 v77, v77, v172, s24
	v_bfe_u32 v172, v79, 16, 1
	v_lshrrev_b32_e32 v77, 16, v77
	v_add3_u32 v79, v79, v172, s24
	v_and_or_b32 v77, v79, s22, v77
	global_store_dword v[206:207], v77, off offset:3328
	v_mul_f32_e32 v77, v75, v192
	v_mul_f32_e32 v79, v75, v194
	v_bfe_u32 v172, v77, 16, 1
	v_add3_u32 v77, v77, v172, s24
	v_bfe_u32 v172, v79, 16, 1
	v_lshrrev_b32_e32 v77, 16, v77
	v_add3_u32 v79, v79, v172, s24
	v_and_or_b32 v77, v79, s22, v77
	global_store_dword v[206:207], v77, off offset:3584
	v_fmamk_f32 v77, v81, 0x3a800000, v102
	v_mul_f32_e32 v79, 0x4f800000, v77
	v_cmp_gt_f32_e32 vcc, s23, v77
	v_mul_f32_e32 v192, 0x4f800000, v155
	v_mul_f32_e32 v81, v75, v191
	v_cndmask_b32_e32 v77, v77, v79, vcc
	v_sqrt_f32_e32 v79, v77
	v_mul_f32_e32 v75, v75, v204
	v_bfe_u32 v172, v81, 16, 1
	v_add3_u32 v81, v81, v172, s24
	v_add_u32_e32 v173, -1, v79
	v_fma_f32 v174, -v173, v79, v77
	v_cmp_ge_f32_e64 s[4:5], 0, v174
	v_add_u32_e32 v174, 1, v79
	v_bfe_u32 v172, v75, 16, 1
	v_cndmask_b32_e64 v173, v79, v173, s[4:5]
	v_fma_f32 v79, -v174, v79, v77
	v_cmp_lt_f32_e64 s[4:5], 0, v79
	v_lshrrev_b32_e32 v81, 16, v81
	v_add3_u32 v75, v75, v172, s24
	v_cndmask_b32_e64 v79, v173, v174, s[4:5]
	v_mul_f32_e32 v173, 0x37800000, v79
	v_cndmask_b32_e32 v79, v79, v173, vcc
	v_cmp_class_f32_e32 vcc, v77, v103
	v_cmp_gt_f32_e64 s[4:5], s23, v155
	v_and_or_b32 v75, v75, s22, v81
	v_cndmask_b32_e32 v77, v79, v77, vcc
	v_div_scale_f32 v79, s[0:1], v77, v77, 1.0
	v_rcp_f32_e32 v173, v79
	v_cndmask_b32_e64 v155, v155, v192, s[4:5]
	v_sqrt_f32_e32 v192, v155
	global_store_dword v[206:207], v75, off offset:3840
	v_fma_f32 v174, -v79, v173, 1.0
	v_fmac_f32_e32 v173, v174, v173
	v_div_scale_f32 v174, vcc, 1.0, v77, 1.0
	v_mul_f32_e32 v191, v174, v173
	v_fma_f32 v193, -v79, v191, v174
	v_fmac_f32_e32 v191, v193, v173
	v_fma_f32 v79, -v79, v191, v174
	v_add_u32_e32 v174, -1, v192
	v_fma_f32 v193, -v174, v192, v155
	v_cmp_ge_f32_e64 s[6:7], 0, v193
	v_add_u32_e32 v193, 1, v192
	v_div_fmas_f32 v79, v79, v173, v191
	v_cndmask_b32_e64 v174, v192, v174, s[6:7]
	v_fma_f32 v192, -v193, v192, v155
	v_cmp_lt_f32_e64 s[6:7], 0, v192
	v_div_fixup_f32 v77, v79, v77, 1.0
	v_fmamk_f32 v27, v27, 0x3a800000, v102
	v_cndmask_b32_e64 v174, v174, v193, s[6:7]
	v_mul_f32_e32 v192, 0x37800000, v174
	v_cndmask_b32_e64 v174, v174, v192, s[4:5]
	v_cmp_class_f32_e64 s[4:5], v155, v103
	v_fmamk_f32 v107, v107, 0x3a800000, v102
	v_fmamk_f32 v23, v23, 0x3a800000, v102
	v_cndmask_b32_e64 v155, v174, v155, s[4:5]
	v_div_scale_f32 v174, s[0:1], v155, v155, 1.0
	v_rcp_f32_e32 v192, v174
	v_fmamk_f32 v106, v106, 0x3a800000, v102
	v_fmamk_f32 v19, v19, 0x3a800000, v102
	v_fmamk_f32 v15, v15, 0x3a800000, v102
	v_fma_f32 v79, -v174, v192, 1.0
	v_fmac_f32_e32 v192, v79, v192
	v_div_scale_f32 v79, vcc, 1.0, v155, 1.0
	v_mul_f32_e32 v173, v79, v192
	v_fma_f32 v191, -v174, v173, v79
	v_fmac_f32_e32 v173, v191, v192
	v_fma_f32 v79, -v174, v173, v79
	v_div_fmas_f32 v79, v79, v192, v173
	v_div_fixup_f32 v79, v79, v155, 1.0
	v_div_scale_f32 v155, s[0:1], v79, v79, v77
	v_rcp_f32_e32 v173, v155
	s_add_i32 s0, s12, 1
	s_ashr_i32 s1, s0, 31
	s_lshl_b64 s[0:1], s[0:1], 12
	v_fma_f32 v75, -v155, v173, 1.0
	v_fmac_f32_e32 v173, v75, v173
	v_div_scale_f32 v75, vcc, v77, v79, v77
	v_mul_f32_e32 v81, v75, v173
	v_fma_f32 v172, -v155, v81, v75
	v_fmac_f32_e32 v81, v172, v173
	v_fma_f32 v75, -v155, v81, v75
	v_div_fmas_f32 v75, v75, v173, v81
	v_div_fixup_f32 v75, v75, v79, v77
	v_mul_f32_e32 v77, v75, v189
	v_mul_f32_e32 v79, v75, v190
	v_bfe_u32 v81, v77, 16, 1
	v_add3_u32 v77, v77, v81, s24
	v_bfe_u32 v81, v79, 16, 1
	v_lshrrev_b32_e32 v77, 16, v77
	v_add3_u32 v79, v79, v81, s24
	v_lshl_add_u64 v[172:173], v[68:69], 0, s[0:1]
	v_and_or_b32 v77, v79, s22, v77
	global_store_dword v[172:173], v77, off offset:2048
	v_mul_f32_e32 v77, v75, v187
	v_mul_f32_e32 v79, v75, v188
	v_bfe_u32 v81, v77, 16, 1
	v_add3_u32 v77, v77, v81, s24
	v_bfe_u32 v81, v79, 16, 1
	v_lshrrev_b32_e32 v77, 16, v77
	v_add3_u32 v79, v79, v81, s24
	v_and_or_b32 v77, v79, s22, v77
	global_store_dword v[172:173], v77, off offset:2304
	v_mul_f32_e32 v77, v75, v185
	v_mul_f32_e32 v79, v75, v186
	v_bfe_u32 v81, v77, 16, 1
	v_add3_u32 v77, v77, v81, s24
	v_bfe_u32 v81, v79, 16, 1
	v_lshrrev_b32_e32 v77, 16, v77
	v_add3_u32 v79, v79, v81, s24
	v_and_or_b32 v77, v79, s22, v77
	global_store_dword v[172:173], v77, off offset:2560
	v_mul_f32_e32 v77, v75, v183
	v_mul_f32_e32 v79, v75, v184
	v_bfe_u32 v81, v77, 16, 1
	v_add3_u32 v77, v77, v81, s24
	v_bfe_u32 v81, v79, 16, 1
	v_lshrrev_b32_e32 v77, 16, v77
	v_add3_u32 v79, v79, v81, s24
	v_and_or_b32 v77, v79, s22, v77
	global_store_dword v[172:173], v77, off offset:2816
	v_mul_f32_e32 v77, v75, v181
	v_mul_f32_e32 v79, v75, v182
	v_bfe_u32 v81, v77, 16, 1
	v_add3_u32 v77, v77, v81, s24
	v_bfe_u32 v81, v79, 16, 1
	v_lshrrev_b32_e32 v77, 16, v77
	v_add3_u32 v79, v79, v81, s24
	v_and_or_b32 v77, v79, s22, v77
	global_store_dword v[172:173], v77, off offset:3072
	v_mul_f32_e32 v77, v75, v179
	v_mul_f32_e32 v79, v75, v180
	v_bfe_u32 v81, v77, 16, 1
	v_add3_u32 v77, v77, v81, s24
	v_bfe_u32 v81, v79, 16, 1
	v_lshrrev_b32_e32 v77, 16, v77
	v_add3_u32 v79, v79, v81, s24
	v_and_or_b32 v77, v79, s22, v77
	global_store_dword v[172:173], v77, off offset:3328
	v_mul_f32_e32 v77, v75, v177
	v_mul_f32_e32 v79, v75, v178
	v_bfe_u32 v81, v77, 16, 1
	v_add3_u32 v77, v77, v81, s24
	v_bfe_u32 v81, v79, 16, 1
	v_lshrrev_b32_e32 v77, 16, v77
	v_add3_u32 v79, v79, v81, s24
	v_and_or_b32 v77, v79, s22, v77
	global_store_dword v[172:173], v77, off offset:3584
	v_fmamk_f32 v77, v205, 0x3a800000, v102
	v_mul_f32_e32 v79, 0x4f800000, v77
	v_cmp_gt_f32_e32 vcc, s23, v77
	v_mul_f32_e32 v81, v75, v175
	v_mul_f32_e32 v177, 0x4f800000, v122
	v_cndmask_b32_e32 v77, v77, v79, vcc
	v_sqrt_f32_e32 v79, v77
	v_mul_f32_e32 v75, v75, v176
	v_bfe_u32 v155, v81, 16, 1
	v_add3_u32 v81, v81, v155, s24
	v_add_u32_e32 v174, -1, v79
	v_fma_f32 v175, -v174, v79, v77
	v_cmp_ge_f32_e64 s[4:5], 0, v175
	v_add_u32_e32 v175, 1, v79
	v_bfe_u32 v155, v75, 16, 1
	v_cndmask_b32_e64 v174, v79, v174, s[4:5]
	v_fma_f32 v79, -v175, v79, v77
	v_cmp_lt_f32_e64 s[4:5], 0, v79
	v_lshrrev_b32_e32 v81, 16, v81
	v_add3_u32 v75, v75, v155, s24
	v_cndmask_b32_e64 v79, v174, v175, s[4:5]
	v_mul_f32_e32 v174, 0x37800000, v79
	v_cndmask_b32_e32 v79, v79, v174, vcc
	v_cmp_class_f32_e32 vcc, v77, v103
	v_cmp_gt_f32_e64 s[4:5], s23, v122
	v_and_or_b32 v75, v75, s22, v81
	v_cndmask_b32_e32 v77, v79, v77, vcc
	v_div_scale_f32 v79, s[0:1], v77, v77, 1.0
	v_rcp_f32_e32 v174, v79
	v_cndmask_b32_e64 v122, v122, v177, s[4:5]
	v_sqrt_f32_e32 v177, v122
	global_store_dword v[172:173], v75, off offset:3840
	v_fma_f32 v175, -v79, v174, 1.0
	v_fmac_f32_e32 v174, v175, v174
	v_div_scale_f32 v175, vcc, 1.0, v77, 1.0
	v_mul_f32_e32 v176, v175, v174
	v_fma_f32 v178, -v79, v176, v175
	v_fmac_f32_e32 v176, v178, v174
	v_fma_f32 v79, -v79, v176, v175
	v_add_u32_e32 v175, -1, v177
	v_fma_f32 v178, -v175, v177, v122
	v_cmp_ge_f32_e64 s[6:7], 0, v178
	v_add_u32_e32 v178, 1, v177
	v_div_fmas_f32 v79, v79, v174, v176
	v_cndmask_b32_e64 v175, v177, v175, s[6:7]
	v_fma_f32 v177, -v178, v177, v122
	v_cmp_lt_f32_e64 s[6:7], 0, v177
	v_div_fixup_f32 v77, v79, v77, 1.0
	s_nop 0
	v_cndmask_b32_e64 v175, v175, v178, s[6:7]
	v_mul_f32_e32 v177, 0x37800000, v175
	v_cndmask_b32_e64 v175, v175, v177, s[4:5]
	v_cmp_class_f32_e64 s[4:5], v122, v103
	s_nop 1
	v_cndmask_b32_e64 v122, v175, v122, s[4:5]
	v_div_scale_f32 v175, s[0:1], v122, v122, 1.0
	v_rcp_f32_e32 v177, v175
	s_nop 0
	v_fma_f32 v79, -v175, v177, 1.0
	v_fmac_f32_e32 v177, v79, v177
	v_div_scale_f32 v79, vcc, 1.0, v122, 1.0
	v_mul_f32_e32 v174, v79, v177
	v_fma_f32 v176, -v175, v174, v79
	v_fmac_f32_e32 v174, v176, v177
	v_fma_f32 v79, -v175, v174, v79
	v_div_fmas_f32 v79, v79, v177, v174
	v_div_fixup_f32 v79, v79, v122, 1.0
	v_div_scale_f32 v122, s[0:1], v79, v79, v77
	v_rcp_f32_e32 v174, v122
	s_add_i32 s0, s12, 2
	s_ashr_i32 s1, s0, 31
	s_lshl_b64 s[0:1], s[0:1], 12
	v_fma_f32 v75, -v122, v174, 1.0
	v_fmac_f32_e32 v174, v75, v174
	v_div_scale_f32 v75, vcc, v77, v79, v77
	v_mul_f32_e32 v81, v75, v174
	v_fma_f32 v155, -v122, v81, v75
	v_fmac_f32_e32 v81, v155, v174
	v_fma_f32 v75, -v122, v81, v75
	v_div_fmas_f32 v75, v75, v174, v81
	v_div_fixup_f32 v75, v75, v79, v77
	v_mul_f32_e32 v77, v75, v170
	v_mul_f32_e32 v79, v75, v171
	v_bfe_u32 v81, v77, 16, 1
	v_add3_u32 v77, v77, v81, s24
	v_bfe_u32 v81, v79, 16, 1
	v_lshrrev_b32_e32 v77, 16, v77
	v_add3_u32 v79, v79, v81, s24
	v_lshl_add_u64 v[172:173], v[68:69], 0, s[0:1]
	v_and_or_b32 v77, v79, s22, v77
	global_store_dword v[172:173], v77, off offset:2048
	v_mul_f32_e32 v77, v75, v168
	v_mul_f32_e32 v79, v75, v169
	v_bfe_u32 v81, v77, 16, 1
	v_add3_u32 v77, v77, v81, s24
	v_bfe_u32 v81, v79, 16, 1
	v_lshrrev_b32_e32 v77, 16, v77
	v_add3_u32 v79, v79, v81, s24
	v_and_or_b32 v77, v79, s22, v77
	global_store_dword v[172:173], v77, off offset:2304
	v_mul_f32_e32 v77, v75, v166
	v_mul_f32_e32 v79, v75, v167
	v_bfe_u32 v81, v77, 16, 1
	v_add3_u32 v77, v77, v81, s24
	v_bfe_u32 v81, v79, 16, 1
	v_lshrrev_b32_e32 v77, 16, v77
	v_add3_u32 v79, v79, v81, s24
	v_and_or_b32 v77, v79, s22, v77
	global_store_dword v[172:173], v77, off offset:2560
	v_mul_f32_e32 v77, v75, v164
	v_mul_f32_e32 v79, v75, v165
	v_bfe_u32 v81, v77, 16, 1
	v_add3_u32 v77, v77, v81, s24
	v_bfe_u32 v81, v79, 16, 1
	v_lshrrev_b32_e32 v77, 16, v77
	v_add3_u32 v79, v79, v81, s24
	v_and_or_b32 v77, v79, s22, v77
	global_store_dword v[172:173], v77, off offset:2816
	v_mul_f32_e32 v77, v75, v162
	v_mul_f32_e32 v79, v75, v163
	v_bfe_u32 v81, v77, 16, 1
	v_add3_u32 v77, v77, v81, s24
	v_bfe_u32 v81, v79, 16, 1
	v_lshrrev_b32_e32 v77, 16, v77
	v_add3_u32 v79, v79, v81, s24
	v_and_or_b32 v77, v79, s22, v77
	global_store_dword v[172:173], v77, off offset:3072
	v_mul_f32_e32 v77, v75, v160
	v_mul_f32_e32 v79, v75, v161
	v_bfe_u32 v81, v77, 16, 1
	v_add3_u32 v77, v77, v81, s24
	v_bfe_u32 v81, v79, 16, 1
	v_lshrrev_b32_e32 v77, 16, v77
	v_add3_u32 v79, v79, v81, s24
	v_and_or_b32 v77, v79, s22, v77
	global_store_dword v[172:173], v77, off offset:3328
	v_mul_f32_e32 v77, v75, v158
	v_mul_f32_e32 v79, v75, v159
	v_bfe_u32 v81, v77, 16, 1
	v_add3_u32 v77, v77, v81, s24
	v_bfe_u32 v81, v79, 16, 1
	v_lshrrev_b32_e32 v77, 16, v77
	v_add3_u32 v79, v79, v81, s24
	v_and_or_b32 v77, v79, s22, v77
	global_store_dword v[172:173], v77, off offset:3584
	v_mul_f32_e32 v77, 0x4f800000, v31
	v_cmp_gt_f32_e32 vcc, s23, v31
	v_mul_f32_e32 v79, v75, v156
	v_mul_f32_e32 v75, v75, v157
	v_cndmask_b32_e32 v31, v31, v77, vcc
	v_sqrt_f32_e32 v77, v31
	v_mul_f32_e32 v157, 0x4f800000, v108
	v_bfe_u32 v81, v79, 16, 1
	v_add3_u32 v79, v79, v81, s24
	v_add_u32_e32 v122, -1, v77
	v_fma_f32 v155, -v122, v77, v31
	v_cmp_ge_f32_e64 s[4:5], 0, v155
	v_add_u32_e32 v155, 1, v77
	v_bfe_u32 v81, v75, 16, 1
	v_cndmask_b32_e64 v122, v77, v122, s[4:5]
	v_fma_f32 v77, -v155, v77, v31
	v_cmp_lt_f32_e64 s[4:5], 0, v77
	v_lshrrev_b32_e32 v79, 16, v79
	v_add3_u32 v75, v75, v81, s24
	v_cndmask_b32_e64 v77, v122, v155, s[4:5]
	v_mul_f32_e32 v122, 0x37800000, v77
	v_cndmask_b32_e32 v77, v77, v122, vcc
	v_cmp_class_f32_e32 vcc, v31, v103
	v_cmp_gt_f32_e64 s[4:5], s23, v108
	v_and_or_b32 v75, v75, s22, v79
	v_cndmask_b32_e32 v31, v77, v31, vcc
	v_div_scale_f32 v77, s[0:1], v31, v31, 1.0
	v_rcp_f32_e32 v122, v77
	v_cndmask_b32_e64 v108, v108, v157, s[4:5]
	v_sqrt_f32_e32 v157, v108
	global_store_dword v[172:173], v75, off offset:3840
	v_fma_f32 v155, -v77, v122, 1.0
	v_fmac_f32_e32 v122, v155, v122
	v_div_scale_f32 v155, vcc, 1.0, v31, 1.0
	v_mul_f32_e32 v156, v155, v122
	v_fma_f32 v158, -v77, v156, v155
	v_fmac_f32_e32 v156, v158, v122
	v_fma_f32 v77, -v77, v156, v155
	v_add_u32_e32 v155, -1, v157
	v_fma_f32 v158, -v155, v157, v108
	v_cmp_ge_f32_e64 s[6:7], 0, v158
	v_add_u32_e32 v158, 1, v157
	v_div_fmas_f32 v77, v77, v122, v156
	v_cndmask_b32_e64 v155, v157, v155, s[6:7]
	v_fma_f32 v157, -v158, v157, v108
	v_cmp_lt_f32_e64 s[6:7], 0, v157
	v_div_fixup_f32 v31, v77, v31, 1.0
	s_nop 0
	v_cndmask_b32_e64 v155, v155, v158, s[6:7]
	v_mul_f32_e32 v157, 0x37800000, v155
	v_cndmask_b32_e64 v155, v155, v157, s[4:5]
	v_cmp_class_f32_e64 s[4:5], v108, v103
	s_nop 1
	v_cndmask_b32_e64 v108, v155, v108, s[4:5]
	v_div_scale_f32 v155, s[0:1], v108, v108, 1.0
	v_rcp_f32_e32 v157, v155
	s_nop 0
	v_fma_f32 v77, -v155, v157, 1.0
	v_fmac_f32_e32 v157, v77, v157
	v_div_scale_f32 v77, vcc, 1.0, v108, 1.0
	v_mul_f32_e32 v122, v77, v157
	v_fma_f32 v156, -v155, v122, v77
	v_fmac_f32_e32 v122, v156, v157
	v_fma_f32 v77, -v155, v122, v77
	v_div_fmas_f32 v77, v77, v157, v122
	v_div_fixup_f32 v77, v77, v108, 1.0
	v_div_scale_f32 v108, s[0:1], v77, v77, v31
	v_rcp_f32_e32 v122, v108
	s_add_i32 s0, s12, 3
	s_ashr_i32 s1, s0, 31
	s_lshl_b64 s[0:1], s[0:1], 12
	v_fma_f32 v75, -v108, v122, 1.0
	v_fmac_f32_e32 v122, v75, v122
	v_div_scale_f32 v75, vcc, v31, v77, v31
	v_mul_f32_e32 v79, v75, v122
	v_fma_f32 v81, -v108, v79, v75
	v_fmac_f32_e32 v79, v81, v122
	v_fma_f32 v75, -v108, v79, v75
	v_div_fmas_f32 v75, v75, v122, v79
	v_div_fixup_f32 v31, v75, v77, v31
	v_mul_f32_e32 v75, v31, v153
	v_mul_f32_e32 v77, v31, v154
	v_bfe_u32 v79, v75, 16, 1
	v_add3_u32 v75, v75, v79, s24
	v_bfe_u32 v79, v77, 16, 1
	v_lshrrev_b32_e32 v75, 16, v75
	v_add3_u32 v77, v77, v79, s24
	v_lshl_add_u64 v[156:157], v[68:69], 0, s[0:1]
	v_and_or_b32 v75, v77, s22, v75
	global_store_dword v[156:157], v75, off offset:2048
	v_mul_f32_e32 v75, v31, v151
	v_mul_f32_e32 v77, v31, v152
	v_bfe_u32 v79, v75, 16, 1
	v_add3_u32 v75, v75, v79, s24
	v_bfe_u32 v79, v77, 16, 1
	v_lshrrev_b32_e32 v75, 16, v75
	v_add3_u32 v77, v77, v79, s24
	v_and_or_b32 v75, v77, s22, v75
	global_store_dword v[156:157], v75, off offset:2304
	v_mul_f32_e32 v75, v31, v149
	v_mul_f32_e32 v77, v31, v150
	v_bfe_u32 v79, v75, 16, 1
	v_add3_u32 v75, v75, v79, s24
	v_bfe_u32 v79, v77, 16, 1
	v_lshrrev_b32_e32 v75, 16, v75
	v_add3_u32 v77, v77, v79, s24
	v_and_or_b32 v75, v77, s22, v75
	global_store_dword v[156:157], v75, off offset:2560
	v_mul_f32_e32 v75, v31, v147
	v_mul_f32_e32 v77, v31, v148
	v_bfe_u32 v79, v75, 16, 1
	v_add3_u32 v75, v75, v79, s24
	v_bfe_u32 v79, v77, 16, 1
	v_lshrrev_b32_e32 v75, 16, v75
	v_add3_u32 v77, v77, v79, s24
	v_and_or_b32 v75, v77, s22, v75
	global_store_dword v[156:157], v75, off offset:2816
	v_mul_f32_e32 v75, v31, v145
	v_mul_f32_e32 v77, v31, v146
	v_bfe_u32 v79, v75, 16, 1
	v_add3_u32 v75, v75, v79, s24
	v_bfe_u32 v79, v77, 16, 1
	v_lshrrev_b32_e32 v75, 16, v75
	v_add3_u32 v77, v77, v79, s24
	v_and_or_b32 v75, v77, s22, v75
	global_store_dword v[156:157], v75, off offset:3072
	v_mul_f32_e32 v75, v31, v143
	v_mul_f32_e32 v77, v31, v144
	v_bfe_u32 v79, v75, 16, 1
	v_add3_u32 v75, v75, v79, s24
	v_bfe_u32 v79, v77, 16, 1
	v_lshrrev_b32_e32 v75, 16, v75
	v_add3_u32 v77, v77, v79, s24
	v_and_or_b32 v75, v77, s22, v75
	global_store_dword v[156:157], v75, off offset:3328
	v_mul_f32_e32 v75, v31, v141
	v_mul_f32_e32 v77, v31, v142
	v_bfe_u32 v79, v75, 16, 1
	v_add3_u32 v75, v75, v79, s24
	v_bfe_u32 v79, v77, 16, 1
	v_lshrrev_b32_e32 v75, 16, v75
	v_add3_u32 v77, v77, v79, s24
	v_and_or_b32 v75, v77, s22, v75
	global_store_dword v[156:157], v75, off offset:3584
	v_mul_f32_e32 v75, 0x4f800000, v27
	v_cmp_gt_f32_e32 vcc, s23, v27
	v_mul_f32_e32 v77, v31, v139
	v_mul_f32_e32 v139, 0x4f800000, v107
	v_cndmask_b32_e32 v27, v27, v75, vcc
	v_sqrt_f32_e32 v75, v27
	v_mul_f32_e32 v31, v31, v140
	v_bfe_u32 v79, v77, 16, 1
	v_add3_u32 v77, v77, v79, s24
	v_add_u32_e32 v81, -1, v75
	v_fma_f32 v108, -v81, v75, v27
	v_cmp_ge_f32_e64 s[4:5], 0, v108
	v_add_u32_e32 v108, 1, v75
	v_bfe_u32 v79, v31, 16, 1
	v_cndmask_b32_e64 v81, v75, v81, s[4:5]
	v_fma_f32 v75, -v108, v75, v27
	v_cmp_lt_f32_e64 s[4:5], 0, v75
	v_lshrrev_b32_e32 v77, 16, v77
	v_add3_u32 v31, v31, v79, s24
	v_cndmask_b32_e64 v75, v81, v108, s[4:5]
	v_mul_f32_e32 v81, 0x37800000, v75
	v_cndmask_b32_e32 v75, v75, v81, vcc
	v_cmp_class_f32_e32 vcc, v27, v103
	v_cmp_gt_f32_e64 s[4:5], s23, v107
	v_and_or_b32 v31, v31, s22, v77
	v_cndmask_b32_e32 v27, v75, v27, vcc
	v_div_scale_f32 v75, s[0:1], v27, v27, 1.0
	v_rcp_f32_e32 v81, v75
	v_cndmask_b32_e64 v107, v107, v139, s[4:5]
	v_sqrt_f32_e32 v139, v107
	global_store_dword v[156:157], v31, off offset:3840
	v_fma_f32 v108, -v75, v81, 1.0
	v_fmac_f32_e32 v81, v108, v81
	v_div_scale_f32 v108, vcc, 1.0, v27, 1.0
	v_mul_f32_e32 v122, v108, v81
	v_fma_f32 v140, -v75, v122, v108
	v_fmac_f32_e32 v122, v140, v81
	v_fma_f32 v75, -v75, v122, v108
	v_add_u32_e32 v108, -1, v139
	v_fma_f32 v140, -v108, v139, v107
	v_cmp_ge_f32_e64 s[6:7], 0, v140
	v_add_u32_e32 v140, 1, v139
	v_div_fmas_f32 v75, v75, v81, v122
	v_cndmask_b32_e64 v108, v139, v108, s[6:7]
	v_fma_f32 v139, -v140, v139, v107
	v_cmp_lt_f32_e64 s[6:7], 0, v139
	v_div_fixup_f32 v27, v75, v27, 1.0
	s_nop 0
	v_cndmask_b32_e64 v108, v108, v140, s[6:7]
	v_mul_f32_e32 v139, 0x37800000, v108
	v_cndmask_b32_e64 v108, v108, v139, s[4:5]
	v_cmp_class_f32_e64 s[4:5], v107, v103
	s_nop 1
	v_cndmask_b32_e64 v107, v108, v107, s[4:5]
	v_div_scale_f32 v108, s[0:1], v107, v107, 1.0
	v_rcp_f32_e32 v139, v108
	s_nop 0
	v_fma_f32 v75, -v108, v139, 1.0
	v_fmac_f32_e32 v139, v75, v139
	v_div_scale_f32 v75, vcc, 1.0, v107, 1.0
	v_mul_f32_e32 v81, v75, v139
	v_fma_f32 v122, -v108, v81, v75
	v_fmac_f32_e32 v81, v122, v139
	v_fma_f32 v75, -v108, v81, v75
	v_div_fmas_f32 v75, v75, v139, v81
	v_div_fixup_f32 v75, v75, v107, 1.0
	v_div_scale_f32 v81, s[0:1], v75, v75, v27
	v_rcp_f32_e32 v107, v81
	s_add_i32 s0, s12, 4
	s_ashr_i32 s1, s0, 31
	s_lshl_b64 s[0:1], s[0:1], 12
	v_fma_f32 v31, -v81, v107, 1.0
	v_fmac_f32_e32 v107, v31, v107
	v_div_scale_f32 v31, vcc, v27, v75, v27
	v_mul_f32_e32 v77, v31, v107
	v_fma_f32 v79, -v81, v77, v31
	v_fmac_f32_e32 v77, v79, v107
	v_fma_f32 v31, -v81, v77, v31
	v_div_fmas_f32 v31, v31, v107, v77
	v_div_fixup_f32 v27, v31, v75, v27
	v_mul_f32_e32 v31, v27, v132
	v_mul_f32_e32 v75, v27, v133
	v_bfe_u32 v77, v31, 16, 1
	v_add3_u32 v31, v31, v77, s24
	v_bfe_u32 v77, v75, 16, 1
	v_lshrrev_b32_e32 v31, 16, v31
	v_add3_u32 v75, v75, v77, s24
	v_lshl_add_u64 v[140:141], v[68:69], 0, s[0:1]
	v_and_or_b32 v31, v75, s22, v31
	global_store_dword v[140:141], v31, off offset:2048
	v_mul_f32_e32 v31, v27, v130
	v_mul_f32_e32 v75, v27, v131
	v_bfe_u32 v77, v31, 16, 1
	v_add3_u32 v31, v31, v77, s24
	v_bfe_u32 v77, v75, 16, 1
	v_lshrrev_b32_e32 v31, 16, v31
	v_add3_u32 v75, v75, v77, s24
	v_and_or_b32 v31, v75, s22, v31
	global_store_dword v[140:141], v31, off offset:2304
	v_mul_f32_e32 v31, v27, v128
	v_mul_f32_e32 v75, v27, v129
	v_bfe_u32 v77, v31, 16, 1
	v_add3_u32 v31, v31, v77, s24
	v_bfe_u32 v77, v75, 16, 1
	v_lshrrev_b32_e32 v31, 16, v31
	v_add3_u32 v75, v75, v77, s24
	v_and_or_b32 v31, v75, s22, v31
	global_store_dword v[140:141], v31, off offset:2560
	v_mul_f32_e32 v31, v27, v126
	v_mul_f32_e32 v75, v27, v127
	v_bfe_u32 v77, v31, 16, 1
	v_add3_u32 v31, v31, v77, s24
	v_bfe_u32 v77, v75, 16, 1
	v_lshrrev_b32_e32 v31, 16, v31
	v_add3_u32 v75, v75, v77, s24
	v_and_or_b32 v31, v75, s22, v31
	global_store_dword v[140:141], v31, off offset:2816
	v_mul_f32_e32 v31, v27, v123
	v_mul_f32_e32 v75, v27, v138
	v_bfe_u32 v77, v31, 16, 1
	v_add3_u32 v31, v31, v77, s24
	v_bfe_u32 v77, v75, 16, 1
	v_lshrrev_b32_e32 v31, 16, v31
	v_add3_u32 v75, v75, v77, s24
	v_and_or_b32 v31, v75, s22, v31
	global_store_dword v[140:141], v31, off offset:3072
	v_mul_f32_e32 v31, v27, v136
	v_mul_f32_e32 v75, v27, v137
	v_bfe_u32 v77, v31, 16, 1
	v_add3_u32 v31, v31, v77, s24
	v_bfe_u32 v77, v75, 16, 1
	v_lshrrev_b32_e32 v31, 16, v31
	v_add3_u32 v75, v75, v77, s24
	v_and_or_b32 v31, v75, s22, v31
	global_store_dword v[140:141], v31, off offset:3328
	v_mul_f32_e32 v31, v27, v134
	v_mul_f32_e32 v75, v27, v135
	v_bfe_u32 v77, v31, 16, 1
	v_add3_u32 v31, v31, v77, s24
	v_bfe_u32 v77, v75, 16, 1
	v_lshrrev_b32_e32 v31, 16, v31
	v_add3_u32 v75, v75, v77, s24
	v_and_or_b32 v31, v75, s22, v31
	global_store_dword v[140:141], v31, off offset:3584
	v_mul_f32_e32 v31, 0x4f800000, v23
	v_cmp_gt_f32_e32 vcc, s23, v23
	v_mul_f32_e32 v108, 0x4f800000, v106
	v_mul_f32_e32 v75, v27, v124
	v_cndmask_b32_e32 v23, v23, v31, vcc
	v_sqrt_f32_e32 v31, v23
	v_mul_f32_e32 v27, v27, v125
	v_bfe_u32 v77, v75, 16, 1
	v_add3_u32 v75, v75, v77, s24
	v_add_u32_e32 v79, -1, v31
	v_fma_f32 v81, -v79, v31, v23
	v_cmp_ge_f32_e64 s[4:5], 0, v81
	v_add_u32_e32 v81, 1, v31
	v_bfe_u32 v77, v27, 16, 1
	v_cndmask_b32_e64 v79, v31, v79, s[4:5]
	v_fma_f32 v31, -v81, v31, v23
	v_cmp_lt_f32_e64 s[4:5], 0, v31
	v_lshrrev_b32_e32 v75, 16, v75
	v_add3_u32 v27, v27, v77, s24
	v_cndmask_b32_e64 v31, v79, v81, s[4:5]
	v_mul_f32_e32 v79, 0x37800000, v31
	v_cndmask_b32_e32 v31, v31, v79, vcc
	v_cmp_class_f32_e32 vcc, v23, v103
	v_cmp_gt_f32_e64 s[4:5], s23, v106
	v_and_or_b32 v27, v27, s22, v75
	v_cndmask_b32_e32 v23, v31, v23, vcc
	v_div_scale_f32 v31, s[0:1], v23, v23, 1.0
	v_rcp_f32_e32 v79, v31
	v_cndmask_b32_e64 v106, v106, v108, s[4:5]
	v_sqrt_f32_e32 v108, v106
	global_store_dword v[140:141], v27, off offset:3840
	v_fma_f32 v81, -v31, v79, 1.0
	v_fmac_f32_e32 v79, v81, v79
	v_div_scale_f32 v81, vcc, 1.0, v23, 1.0
	v_mul_f32_e32 v107, v81, v79
	v_fma_f32 v122, -v31, v107, v81
	v_fmac_f32_e32 v107, v122, v79
	v_fma_f32 v31, -v31, v107, v81
	v_add_u32_e32 v81, -1, v108
	v_fma_f32 v122, -v81, v108, v106
	v_cmp_ge_f32_e64 s[6:7], 0, v122
	v_add_u32_e32 v122, 1, v108
	v_div_fmas_f32 v31, v31, v79, v107
	v_cndmask_b32_e64 v81, v108, v81, s[6:7]
	v_fma_f32 v108, -v122, v108, v106
	v_cmp_lt_f32_e64 s[6:7], 0, v108
	v_div_fixup_f32 v23, v31, v23, 1.0
	s_nop 0
	v_cndmask_b32_e64 v81, v81, v122, s[6:7]
	v_mul_f32_e32 v108, 0x37800000, v81
	v_cndmask_b32_e64 v81, v81, v108, s[4:5]
	v_cmp_class_f32_e64 s[4:5], v106, v103
	s_nop 1
	v_cndmask_b32_e64 v81, v81, v106, s[4:5]
	v_div_scale_f32 v106, s[0:1], v81, v81, 1.0
	v_rcp_f32_e32 v108, v106
	s_nop 0
	v_fma_f32 v31, -v106, v108, 1.0
	v_fmac_f32_e32 v108, v31, v108
	v_div_scale_f32 v31, vcc, 1.0, v81, 1.0
	v_mul_f32_e32 v79, v31, v108
	v_fma_f32 v107, -v106, v79, v31
	v_fmac_f32_e32 v79, v107, v108
	v_fma_f32 v31, -v106, v79, v31
	v_div_fmas_f32 v31, v31, v108, v79
	v_div_fixup_f32 v31, v31, v81, 1.0
	v_div_scale_f32 v79, s[0:1], v31, v31, v23
	v_rcp_f32_e32 v81, v79
	s_add_i32 s0, s12, 5
	s_ashr_i32 s1, s0, 31
	s_lshl_b64 s[0:1], s[0:1], 12
	v_fma_f32 v27, -v79, v81, 1.0
	v_fmac_f32_e32 v81, v27, v81
	v_div_scale_f32 v27, vcc, v23, v31, v23
	v_mul_f32_e32 v75, v27, v81
	v_fma_f32 v77, -v79, v75, v27
	v_fmac_f32_e32 v75, v77, v81
	v_fma_f32 v27, -v79, v75, v27
	v_div_fmas_f32 v27, v27, v81, v75
	v_div_fixup_f32 v23, v27, v31, v23
	v_mul_f32_e32 v27, v23, v120
	v_mul_f32_e32 v31, v23, v121
	v_bfe_u32 v75, v27, 16, 1
	v_add3_u32 v27, v27, v75, s24
	v_bfe_u32 v75, v31, 16, 1
	v_lshrrev_b32_e32 v27, 16, v27
	v_add3_u32 v31, v31, v75, s24
	v_lshl_add_u64 v[106:107], v[68:69], 0, s[0:1]
	v_and_or_b32 v27, v31, s22, v27
	global_store_dword v[106:107], v27, off offset:2048
	v_mul_f32_e32 v27, v23, v118
	v_mul_f32_e32 v31, v23, v119
	v_bfe_u32 v75, v27, 16, 1
	v_add3_u32 v27, v27, v75, s24
	v_bfe_u32 v75, v31, 16, 1
	v_lshrrev_b32_e32 v27, 16, v27
	v_add3_u32 v31, v31, v75, s24
	v_and_or_b32 v27, v31, s22, v27
	global_store_dword v[106:107], v27, off offset:2304
	v_mul_f32_e32 v27, v23, v116
	v_mul_f32_e32 v31, v23, v117
	v_bfe_u32 v75, v27, 16, 1
	v_add3_u32 v27, v27, v75, s24
	v_bfe_u32 v75, v31, 16, 1
	v_lshrrev_b32_e32 v27, 16, v27
	v_add3_u32 v31, v31, v75, s24
	v_and_or_b32 v27, v31, s22, v27
	global_store_dword v[106:107], v27, off offset:2560
	v_mul_f32_e32 v27, v23, v114
	v_mul_f32_e32 v31, v23, v115
	v_bfe_u32 v75, v27, 16, 1
	v_add3_u32 v27, v27, v75, s24
	v_bfe_u32 v75, v31, 16, 1
	v_lshrrev_b32_e32 v27, 16, v27
	v_add3_u32 v31, v31, v75, s24
	v_and_or_b32 v27, v31, s22, v27
	global_store_dword v[106:107], v27, off offset:2816
	v_mul_f32_e32 v27, v23, v112
	v_mul_f32_e32 v31, v23, v113
	v_bfe_u32 v75, v27, 16, 1
	v_add3_u32 v27, v27, v75, s24
	v_bfe_u32 v75, v31, 16, 1
	v_lshrrev_b32_e32 v27, 16, v27
	v_add3_u32 v31, v31, v75, s24
	v_and_or_b32 v27, v31, s22, v27
	global_store_dword v[106:107], v27, off offset:3072
	v_mul_f32_e32 v27, v23, v110
	v_mul_f32_e32 v31, v23, v111
	v_bfe_u32 v75, v27, 16, 1
	v_add3_u32 v27, v27, v75, s24
	v_bfe_u32 v75, v31, 16, 1
	v_lshrrev_b32_e32 v27, 16, v27
	v_add3_u32 v31, v31, v75, s24
	v_and_or_b32 v27, v31, s22, v27
	global_store_dword v[106:107], v27, off offset:3328
	v_mul_f32_e32 v27, v23, v80
	v_mul_f32_e32 v31, v23, v109
	v_bfe_u32 v75, v27, 16, 1
	v_add3_u32 v27, v27, v75, s24
	v_bfe_u32 v75, v31, 16, 1
	v_lshrrev_b32_e32 v27, 16, v27
	v_add3_u32 v31, v31, v75, s24
	v_and_or_b32 v27, v31, s22, v27
	global_store_dword v[106:107], v27, off offset:3584
	v_mul_f32_e32 v27, 0x4f800000, v19
	v_cmp_gt_f32_e32 vcc, s23, v19
	v_mul_f32_e32 v31, v23, v76
	v_fmamk_f32 v79, v105, 0x3a800000, v102
	v_cndmask_b32_e32 v19, v19, v27, vcc
	v_sqrt_f32_e32 v27, v19
	v_mul_f32_e32 v80, 0x4f800000, v79
	v_mul_f32_e32 v23, v23, v78
	v_bfe_u32 v75, v31, 16, 1
	v_add_u32_e32 v76, -1, v27
	v_fma_f32 v77, -v76, v27, v19
	v_cmp_ge_f32_e64 s[4:5], 0, v77
	v_add_u32_e32 v77, 1, v27
	v_add3_u32 v31, v31, v75, s24
	v_cndmask_b32_e64 v76, v27, v76, s[4:5]
	v_fma_f32 v27, -v77, v27, v19
	v_cmp_lt_f32_e64 s[4:5], 0, v27
	v_bfe_u32 v75, v23, 16, 1
	v_lshrrev_b32_e32 v31, 16, v31
	v_cndmask_b32_e64 v27, v76, v77, s[4:5]
	v_mul_f32_e32 v76, 0x37800000, v27
	v_cndmask_b32_e32 v27, v27, v76, vcc
	v_cmp_class_f32_e32 vcc, v19, v103
	v_cmp_gt_f32_e64 s[4:5], s23, v79
	v_add3_u32 v23, v23, v75, s24
	v_cndmask_b32_e32 v19, v27, v19, vcc
	v_div_scale_f32 v27, s[0:1], v19, v19, 1.0
	v_rcp_f32_e32 v76, v27
	v_cndmask_b32_e64 v79, v79, v80, s[4:5]
	v_sqrt_f32_e32 v80, v79
	v_and_or_b32 v23, v23, s22, v31
	v_fma_f32 v77, -v27, v76, 1.0
	v_fmac_f32_e32 v76, v77, v76
	v_div_scale_f32 v77, vcc, 1.0, v19, 1.0
	v_mul_f32_e32 v78, v77, v76
	v_fma_f32 v81, -v27, v78, v77
	v_fmac_f32_e32 v78, v81, v76
	v_fma_f32 v27, -v27, v78, v77
	v_add_u32_e32 v77, -1, v80
	v_fma_f32 v81, -v77, v80, v79
	v_cmp_ge_f32_e64 s[6:7], 0, v81
	v_add_u32_e32 v81, 1, v80
	v_div_fmas_f32 v27, v27, v76, v78
	v_cndmask_b32_e64 v77, v80, v77, s[6:7]
	v_fma_f32 v80, -v81, v80, v79
	v_cmp_lt_f32_e64 s[6:7], 0, v80
	v_div_fixup_f32 v19, v27, v19, 1.0
	global_store_dword v[106:107], v23, off offset:3840
	v_cndmask_b32_e64 v77, v77, v81, s[6:7]
	v_mul_f32_e32 v80, 0x37800000, v77
	v_cndmask_b32_e64 v77, v77, v80, s[4:5]
	v_cmp_class_f32_e64 s[4:5], v79, v103
	s_nop 1
	v_cndmask_b32_e64 v77, v77, v79, s[4:5]
	v_div_scale_f32 v79, s[0:1], v77, v77, 1.0
	v_rcp_f32_e32 v80, v79
	s_nop 0
	v_fma_f32 v27, -v79, v80, 1.0
	v_fmac_f32_e32 v80, v27, v80
	v_div_scale_f32 v27, vcc, 1.0, v77, 1.0
	v_mul_f32_e32 v76, v27, v80
	v_fma_f32 v78, -v79, v76, v27
	v_fmac_f32_e32 v76, v78, v80
	v_fma_f32 v27, -v79, v76, v27
	v_div_fmas_f32 v27, v27, v80, v76
	v_div_fixup_f32 v27, v27, v77, 1.0
	v_div_scale_f32 v76, s[0:1], v27, v27, v19
	v_rcp_f32_e32 v77, v76
	s_add_i32 s0, s12, 6
	s_ashr_i32 s1, s0, 31
	s_lshl_b64 s[0:1], s[0:1], 12
	v_fma_f32 v23, -v76, v77, 1.0
	v_fmac_f32_e32 v77, v23, v77
	v_div_scale_f32 v23, vcc, v19, v27, v19
	v_mul_f32_e32 v31, v23, v77
	v_fma_f32 v75, -v76, v31, v23
	v_fmac_f32_e32 v31, v75, v77
	v_fma_f32 v23, -v76, v31, v23
	v_div_fmas_f32 v23, v23, v77, v31
	v_div_fixup_f32 v19, v23, v27, v19
	v_mul_f32_e32 v23, v19, v73
	v_mul_f32_e32 v27, v19, v74
	v_bfe_u32 v31, v23, 16, 1
	v_add3_u32 v23, v23, v31, s24
	v_bfe_u32 v31, v27, 16, 1
	v_lshrrev_b32_e32 v23, 16, v23
	v_add3_u32 v27, v27, v31, s24
	v_lshl_add_u64 v[76:77], v[68:69], 0, s[0:1]
	v_and_or_b32 v23, v27, s22, v23
	global_store_dword v[76:77], v23, off offset:2048
	v_mul_f32_e32 v23, v19, v71
	v_mul_f32_e32 v27, v19, v72
	v_bfe_u32 v31, v23, 16, 1
	v_add3_u32 v23, v23, v31, s24
	v_bfe_u32 v31, v27, 16, 1
	v_lshrrev_b32_e32 v23, 16, v23
	v_add3_u32 v27, v27, v31, s24
	v_and_or_b32 v23, v27, s22, v23
	global_store_dword v[76:77], v23, off offset:2304
	v_mul_f32_e32 v23, v19, v30
	v_mul_f32_e32 v27, v19, v70
	v_bfe_u32 v30, v23, 16, 1
	v_add3_u32 v23, v23, v30, s24
	v_bfe_u32 v30, v27, 16, 1
	v_lshrrev_b32_e32 v23, 16, v23
	v_add3_u32 v27, v27, v30, s24
	v_and_or_b32 v23, v27, s22, v23
	global_store_dword v[76:77], v23, off offset:2560
	v_mul_f32_e32 v23, v19, v28
	v_mul_f32_e32 v27, v19, v29
	v_bfe_u32 v28, v23, 16, 1
	v_add3_u32 v23, v23, v28, s24
	v_bfe_u32 v28, v27, 16, 1
	v_lshrrev_b32_e32 v23, 16, v23
	v_add3_u32 v27, v27, v28, s24
	v_and_or_b32 v23, v27, s22, v23
	global_store_dword v[76:77], v23, off offset:2816
	v_mul_f32_e32 v23, v19, v25
	v_mul_f32_e32 v25, v19, v26
	v_bfe_u32 v26, v23, 16, 1
	v_add3_u32 v23, v23, v26, s24
	v_bfe_u32 v26, v25, 16, 1
	v_lshrrev_b32_e32 v23, 16, v23
	v_add3_u32 v25, v25, v26, s24
	v_and_or_b32 v23, v25, s22, v23
	v_mul_f32_e32 v22, v19, v22
	global_store_dword v[76:77], v23, off offset:3072
	v_mul_f32_e32 v23, v19, v24
	v_bfe_u32 v24, v22, 16, 1
	v_add3_u32 v22, v22, v24, s24
	v_bfe_u32 v24, v23, 16, 1
	v_lshrrev_b32_e32 v22, 16, v22
	v_add3_u32 v23, v23, v24, s24
	v_and_or_b32 v22, v23, s22, v22
	v_mul_f32_e32 v20, v19, v20
	global_store_dword v[76:77], v22, off offset:3328
	v_mul_f32_e32 v21, v19, v21
	v_bfe_u32 v22, v20, 16, 1
	v_add3_u32 v20, v20, v22, s24
	v_bfe_u32 v22, v21, 16, 1
	v_lshrrev_b32_e32 v20, 16, v20
	v_add3_u32 v21, v21, v22, s24
	v_and_or_b32 v20, v21, s22, v20
	global_store_dword v[76:77], v20, off offset:3584
	v_mul_f32_e32 v20, 0x4f800000, v15
	v_cmp_gt_f32_e32 vcc, s23, v15
	v_fmamk_f32 v24, v104, 0x3a800000, v102
	v_mul_f32_e32 v25, 0x4f800000, v24
	v_cndmask_b32_e32 v15, v15, v20, vcc
	v_sqrt_f32_e32 v20, v15
	v_mul_f32_e32 v17, v19, v17
	v_mul_f32_e32 v18, v19, v18
	v_bfe_u32 v19, v17, 16, 1
	v_add_u32_e32 v21, -1, v20
	v_fma_f32 v22, -v21, v20, v15
	v_cmp_ge_f32_e64 s[4:5], 0, v22
	v_add_u32_e32 v22, 1, v20
	v_add3_u32 v17, v17, v19, s24
	v_cndmask_b32_e64 v21, v20, v21, s[4:5]
	v_fma_f32 v20, -v22, v20, v15
	v_cmp_lt_f32_e64 s[4:5], 0, v20
	v_bfe_u32 v19, v18, 16, 1
	v_lshrrev_b32_e32 v17, 16, v17
	v_cndmask_b32_e64 v20, v21, v22, s[4:5]
	v_mul_f32_e32 v21, 0x37800000, v20
	v_cndmask_b32_e32 v20, v20, v21, vcc
	v_cmp_class_f32_e32 vcc, v15, v103
	v_cmp_gt_f32_e64 s[4:5], s23, v24
	v_add3_u32 v18, v18, v19, s24
	v_cndmask_b32_e32 v15, v20, v15, vcc
	v_div_scale_f32 v20, s[0:1], v15, v15, 1.0
	v_rcp_f32_e32 v21, v20
	v_cndmask_b32_e64 v24, v24, v25, s[4:5]
	v_sqrt_f32_e32 v25, v24
	v_and_or_b32 v17, v18, s22, v17
	v_fma_f32 v22, -v20, v21, 1.0
	v_fmac_f32_e32 v21, v22, v21
	v_div_scale_f32 v22, vcc, 1.0, v15, 1.0
	v_mul_f32_e32 v23, v22, v21
	v_fma_f32 v26, -v20, v23, v22
	v_fmac_f32_e32 v23, v26, v21
	v_fma_f32 v20, -v20, v23, v22
	v_add_u32_e32 v22, -1, v25
	v_fma_f32 v26, -v22, v25, v24
	v_cmp_ge_f32_e64 s[6:7], 0, v26
	v_add_u32_e32 v26, 1, v25
	v_div_fmas_f32 v20, v20, v21, v23
	v_cndmask_b32_e64 v22, v25, v22, s[6:7]
	v_fma_f32 v25, -v26, v25, v24
	v_cmp_lt_f32_e64 s[6:7], 0, v25
	v_div_fixup_f32 v15, v20, v15, 1.0
	global_store_dword v[76:77], v17, off offset:3840
	v_cndmask_b32_e64 v22, v22, v26, s[6:7]
	v_mul_f32_e32 v25, 0x37800000, v22
	v_cndmask_b32_e64 v22, v22, v25, s[4:5]
	v_cmp_class_f32_e64 s[4:5], v24, v103
	s_nop 1
	v_cndmask_b32_e64 v22, v22, v24, s[4:5]
	v_div_scale_f32 v24, s[0:1], v22, v22, 1.0
	v_rcp_f32_e32 v25, v24
	s_nop 0
	v_fma_f32 v20, -v24, v25, 1.0
	v_fmac_f32_e32 v25, v20, v25
	v_div_scale_f32 v20, vcc, 1.0, v22, 1.0
	v_mul_f32_e32 v21, v20, v25
	v_fma_f32 v23, -v24, v21, v20
	v_fmac_f32_e32 v21, v23, v25
	v_fma_f32 v20, -v24, v21, v20
	v_div_fmas_f32 v20, v20, v25, v21
	v_div_fixup_f32 v20, v20, v22, 1.0
	v_div_scale_f32 v21, s[0:1], v20, v20, v15
	v_rcp_f32_e32 v22, v21
	s_add_i32 s0, s12, 7
	s_ashr_i32 s1, s0, 31
	s_lshl_b64 s[0:1], s[0:1], 12
	v_fma_f32 v17, -v21, v22, 1.0
	v_fmac_f32_e32 v22, v17, v22
	v_div_scale_f32 v17, vcc, v15, v20, v15
	v_mul_f32_e32 v18, v17, v22
	v_fma_f32 v19, -v21, v18, v17
	v_fmac_f32_e32 v18, v19, v22
	v_fma_f32 v17, -v21, v18, v17
	v_div_fmas_f32 v17, v17, v22, v18
	v_div_fixup_f32 v15, v17, v20, v15
	v_mul_f32_e32 v14, v15, v14
	v_mul_f32_e32 v16, v15, v16
	v_bfe_u32 v17, v14, 16, 1
	v_add3_u32 v14, v14, v17, s24
	v_bfe_u32 v17, v16, 16, 1
	v_lshrrev_b32_e32 v14, 16, v14
	v_add3_u32 v16, v16, v17, s24
	v_lshl_add_u64 v[18:19], v[68:69], 0, s[0:1]
	v_and_or_b32 v14, v16, s22, v14
	v_mul_f32_e32 v12, v15, v12
	global_store_dword v[18:19], v14, off offset:2048
	v_mul_f32_e32 v13, v15, v13
	v_bfe_u32 v14, v12, 16, 1
	v_add3_u32 v12, v12, v14, s24
	v_bfe_u32 v14, v13, 16, 1
	v_lshrrev_b32_e32 v12, 16, v12
	v_add3_u32 v13, v13, v14, s24
	v_and_or_b32 v12, v13, s22, v12
	v_mul_f32_e32 v10, v15, v10
	global_store_dword v[18:19], v12, off offset:2304
	v_mul_f32_e32 v11, v15, v11
	v_bfe_u32 v12, v10, 16, 1
	v_add3_u32 v10, v10, v12, s24
	v_bfe_u32 v12, v11, 16, 1
	v_lshrrev_b32_e32 v10, 16, v10
	v_add3_u32 v11, v11, v12, s24
	v_and_or_b32 v10, v11, s22, v10
	v_mul_f32_e32 v8, v15, v8
	global_store_dword v[18:19], v10, off offset:2560
	v_mul_f32_e32 v9, v15, v9
	v_bfe_u32 v10, v8, 16, 1
	v_add3_u32 v8, v8, v10, s24
	v_bfe_u32 v10, v9, 16, 1
	v_lshrrev_b32_e32 v8, 16, v8
	v_add3_u32 v9, v9, v10, s24
	v_and_or_b32 v8, v9, s22, v8
	v_mul_f32_e32 v6, v15, v6
	global_store_dword v[18:19], v8, off offset:2816
	v_mul_f32_e32 v7, v15, v7
	v_bfe_u32 v8, v6, 16, 1
	v_add3_u32 v6, v6, v8, s24
	v_bfe_u32 v8, v7, 16, 1
	v_lshrrev_b32_e32 v6, 16, v6
	v_add3_u32 v7, v7, v8, s24
	v_and_or_b32 v6, v7, s22, v6
	v_mul_f32_e32 v4, v15, v4
	global_store_dword v[18:19], v6, off offset:3072
	v_mul_f32_e32 v5, v15, v5
	v_bfe_u32 v6, v4, 16, 1
	v_add3_u32 v4, v4, v6, s24
	v_bfe_u32 v6, v5, 16, 1
	v_lshrrev_b32_e32 v4, 16, v4
	v_add3_u32 v5, v5, v6, s24
	v_and_or_b32 v4, v5, s22, v4
	v_mul_f32_e32 v2, v15, v2
	global_store_dword v[18:19], v4, off offset:3328
	v_mul_f32_e32 v3, v15, v3
	v_bfe_u32 v4, v2, 16, 1
	v_add3_u32 v2, v2, v4, s24
	v_bfe_u32 v4, v3, 16, 1
	v_lshrrev_b32_e32 v2, 16, v2
	v_add3_u32 v3, v3, v4, s24
	v_and_or_b32 v2, v3, s22, v2
	v_mul_f32_e32 v0, v15, v0
	global_store_dword v[18:19], v2, off offset:3584
	v_mul_f32_e32 v1, v15, v1
	v_bfe_u32 v2, v0, 16, 1
	v_add3_u32 v0, v0, v2, s24
	v_bfe_u32 v2, v1, 16, 1
	v_lshrrev_b32_e32 v0, 16, v0
	v_add3_u32 v1, v1, v2, s24
	v_and_or_b32 v0, v1, s22, v0
	s_cmpk_lt_i32 s15, 0x100
	global_store_dword v[18:19], v0, off offset:3840
	s_waitcnt vmcnt(63) expcnt(7) lgkmcnt(15)
	s_barrier
	s_cbranch_scc1 .LBB0_474
